# plus first K-loop iteration peeled with C=0 so the 128 accumulator zero-inits per tile are gone
# speedup vs baseline: 1.0056x; 1.0056x over previous
; #define PG8_STAGE(bufoff, gbase, voff) do { _Pragma("unroll") for (int _i = 0; _i < 2; ++_i) \
;         __builtin_amdgcn_global_load_lds((const unsigned*)((const char*)(gbase) + (voff)[_i]), (PG8_LAS unsigned*)(lds + (bufoff) + ldsw + _i * 8192), 16, 0, 0); } while (0)
; #define PG8_LDA(dst, b, h) do { _Pragma("unroll") for (int m = 0; m < 4; ++m) _Pragma("unroll") for (int k = 0; k < 2; ++k) dst[m][k] = *(const PG8_LAS bf16x8*)(lds + PG8_SA(b, h) + aoff + m * 2048 + k * 1024); } while (0)
; #define PG8_LDB(dst, b, h) do { _Pragma("unroll") for (int n = 0; n < 2; ++n) _Pragma("unroll") for (int k = 0; k < 2; ++k) dst[n][k] = *(const PG8_LAS bf16x8*)(lds + PG8_SB(b, h) + boff + n * 2048 + k * 1024); } while (0)
; #define PG8_MMA(ai, bj, At, Bt) do { __builtin_amdgcn_s_setprio(1); _Pragma("unroll") for (int m = 0; m < 4; ++m) _Pragma("unroll") for (int n = 0; n < 2; ++n) _Pragma("unroll") for (int k = 0; k < 2; ++k) \
;         acc[ai][bj][m][n] = __builtin_amdgcn_mfma_f32_16x16x32_bf16(Bt[n][k], At[m][k], acc[ai][bj][m][n], 0, 0, 0); __builtin_amdgcn_s_setprio(0); } while (0)
; #define PG8_WAIT_V(n) asm volatile("s_waitcnt vmcnt(" #n ")" ::: "memory")
; #define PG8_WAIT_L(n) asm volatile("s_waitcnt lgkmcnt(" #n ")" ::: "memory")
; template <class Epi, class Sched, bool ALIGN_EPI = false, bool SP2 = false>
; __device__ __forceinline__ void gemm_phase(PG8_LAS unsigned char* lds, const int Kdim, const Sched& S, const Epi& E) {
;     ...
;         for (int t = 0; t < nt; t += 2) {
;             const bool last = (t == nt - 2);
;             const char* a1 = cA + (size_t)(t + 1) * kstep;
;             const char* a2 = last ? nA : cA + (size_t)(t + 2) * kstep; const char* b2 = last ? nB : cB + (size_t)(t + 2) * kstep;
;             const char* a3 = a2 + kstep; const char* b3 = b2 + kstep;
;             if constexpr (SP2) {
;             PG8_LDB(B0, 0, 0); PG8_LDB(B1, 0, 1); PG8_SCHED; PG8_LDA(At, 0, 0); PG8_STAGE(PG8_SA(1, 1), a1 + hstep, voffA);
;             PG8_WAIT_V(8); PG8_WAIT_L(0); PG8_BAR; PG8_MMA(0, 0, At, B0); PG8_MMA(0, 1, At, B1); PG8_BAR; PG8_SCHED;
;             PG8_LDA(At, 0, 1); PG8_STAGE(PG8_SB(0, 0), b2, voffB); PG8_STAGE(PG8_SB(0, 1), b2 + hstep, voffB); PG8_STAGE(PG8_SA(0, 0), a2, voffA);
;             PG8_WAIT_V(8); PG8_WAIT_L(0); PG8_BAR; PG8_MMA(1, 0, At, B0); PG8_MMA(1, 1, At, B1); PG8_BAR; PG8_SCHED;
.LBB0_221:
	s_and_b64 s[8:9], s[2:3], exec
	s_cselect_b32 s10, s27, s5
	s_cselect_b32 s11, s26, s4
	s_cselect_b32 s12, s31, s7
	s_cselect_b32 s13, s30, s6
	s_add_u32 s4, s4, 0x40080
	s_addc_u32 s5, s5, 0
	v_add_u32_e32 v2, s64, v2
	s_add_u32 s25, s6, 0x100
	s_addc_u32 s29, s7, 0
	s_mov_b32 s34, -2
	v_add_u32_e32 v134, s53, v1
	v_add_u32_e32 v135, s56, v1
	v_add_u32_e32 v136, s41, v2
	v_add_u32_e32 v137, s67, v1
	v_add_u32_e32 v138, s72, v1
	v_mov_b32_e32 v133, v189
	v_mov_b32_e32 v129, v189
	v_mov_b32_e32 v131, v189
	ds_read_b128 v[140:143], v134
	ds_read_b128 v[148:151], v134 offset:1024
	ds_read_b128 v[156:159], v134 offset:2048
	ds_read_b128 v[160:163], v134 offset:3072
	ds_read_b128 v[164:167], v135
	ds_read_b128 v[168:171], v135 offset:1024
	ds_read_b128 v[172:175], v135 offset:2048
	ds_read_b128 v[176:179], v135 offset:3072
	s_add_u32 s6, s4, 0xfffc0080
	s_addc_u32 s7, s5, -1
	s_cmp_eq_u32 s34, 12
	s_cselect_b32 s9, s10, s7
	s_cselect_b32 s8, s11, s6
	s_cselect_b32 s7, s12, s29
	s_cselect_b32 s6, s13, s25
	v_lshl_add_u64 v[144:145], s[4:5], 0, v[188:189]
	s_add_i32 m0, s59, 0xc000
	ds_read_b128 v[180:183], v136
	ds_read_b128 v[184:187], v136 offset:1024
	ds_read_b128 v[194:197], v136 offset:2048
	ds_read_b128 v[198:201], v136 offset:3072
	ds_read_b128 v[212:215], v136 offset:4096
	ds_read_b128 v[216:219], v136 offset:5120
	ds_read_b128 v[220:223], v136 offset:6144
	ds_read_b128 v[224:227], v136 offset:7168
	global_load_lds_dwordx4 v[144:145], off
	v_lshl_add_u64 v[144:145], s[4:5], 0, v[132:133]
	s_add_i32 m0, s59, 0xe000
	s_nop 0
	global_load_lds_dwordx4 v[144:145], off
	s_waitcnt vmcnt(8)
	s_waitcnt lgkmcnt(0)
	s_barrier
	s_setprio 1
	s_waitcnt lgkmcnt(0)
	v_mfma_f32_16x16x32_bf16 v[124:127], v[140:143], v[180:183], 0
	v_mfma_f32_16x16x32_bf16 v[120:123], v[156:159], v[180:183], 0
	v_mfma_f32_16x16x32_bf16 v[108:111], v[140:143], v[194:197], 0
	v_mfma_f32_16x16x32_bf16 v[104:107], v[156:159], v[194:197], 0
	v_mfma_f32_16x16x32_bf16 v[92:95], v[140:143], v[212:215], 0
	v_mfma_f32_16x16x32_bf16 v[88:91], v[156:159], v[212:215], 0
	v_mfma_f32_16x16x32_bf16 v[76:79], v[140:143], v[220:223], 0
	v_mfma_f32_16x16x32_bf16 v[72:75], v[156:159], v[220:223], 0
	v_mfma_f32_16x16x32_bf16 v[124:127], v[148:151], v[184:187], v[124:127]
	v_mfma_f32_16x16x32_bf16 v[120:123], v[160:163], v[184:187], v[120:123]
	v_mfma_f32_16x16x32_bf16 v[108:111], v[148:151], v[198:201], v[108:111]
	v_mfma_f32_16x16x32_bf16 v[104:107], v[160:163], v[198:201], v[104:107]
	v_mfma_f32_16x16x32_bf16 v[92:95], v[148:151], v[216:219], v[92:95]
	v_mfma_f32_16x16x32_bf16 v[88:91], v[160:163], v[216:219], v[88:91]
	v_mfma_f32_16x16x32_bf16 v[76:79], v[148:151], v[224:227], v[76:79]
	v_mfma_f32_16x16x32_bf16 v[72:75], v[160:163], v[224:227], v[72:75]
	v_mfma_f32_16x16x32_bf16 v[116:119], v[164:167], v[180:183], 0
	v_mfma_f32_16x16x32_bf16 v[112:115], v[172:175], v[180:183], 0
	v_mfma_f32_16x16x32_bf16 v[100:103], v[164:167], v[194:197], 0
	v_mfma_f32_16x16x32_bf16 v[96:99], v[172:175], v[194:197], 0
	v_mfma_f32_16x16x32_bf16 v[84:87], v[164:167], v[212:215], 0
	v_mfma_f32_16x16x32_bf16 v[80:83], v[172:175], v[212:215], 0
	v_mfma_f32_16x16x32_bf16 v[68:71], v[164:167], v[220:223], 0
	v_mfma_f32_16x16x32_bf16 v[64:67], v[172:175], v[220:223], 0
	v_mfma_f32_16x16x32_bf16 v[116:119], v[168:171], v[184:187], v[116:119]
	v_mfma_f32_16x16x32_bf16 v[112:115], v[176:179], v[184:187], v[112:115]
	v_mfma_f32_16x16x32_bf16 v[100:103], v[168:171], v[198:201], v[100:103]
	v_mfma_f32_16x16x32_bf16 v[96:99], v[176:179], v[198:201], v[96:99]
	v_mfma_f32_16x16x32_bf16 v[84:87], v[168:171], v[216:219], v[84:87]
	v_mfma_f32_16x16x32_bf16 v[80:83], v[176:179], v[216:219], v[80:83]
	v_mfma_f32_16x16x32_bf16 v[68:71], v[168:171], v[224:227], v[68:71]
	v_mfma_f32_16x16x32_bf16 v[64:67], v[176:179], v[224:227], v[64:67]
	s_setprio 0
	s_barrier
	s_mov_b32 m0, s54
	v_lshl_add_u64 v[144:145], s[6:7], 0, v[128:129]
	s_add_u32 s36, s6, 0x40000
	ds_read_b128 v[180:183], v136 offset:16384
	ds_read_b128 v[184:187], v136 offset:17408
	ds_read_b128 v[194:197], v136 offset:18432
	ds_read_b128 v[198:201], v136 offset:19456
	ds_read_b128 v[212:215], v136 offset:20480
	ds_read_b128 v[216:219], v136 offset:21504
	ds_read_b128 v[220:223], v136 offset:22528
	ds_read_b128 v[224:227], v136 offset:23552
	global_load_lds_dwordx4 v[144:145], off
	v_lshl_add_u64 v[202:203], s[6:7], 0, v[130:131]
	s_mov_b32 m0, s55
	s_addc_u32 s37, s7, 0
	global_load_lds_dwordx4 v[202:203], off
	v_lshl_add_u64 v[228:229], s[36:37], 0, v[128:129]
	s_mov_b32 m0, s57
	v_lshl_add_u64 v[230:231], s[8:9], 0, v[132:133]
	global_load_lds_dwordx4 v[228:229], off
	v_lshl_add_u64 v[228:229], s[36:37], 0, v[130:131]
	s_mov_b32 m0, s58
	s_nop 0
	global_load_lds_dwordx4 v[228:229], off
	v_lshl_add_u64 v[228:229], s[8:9], 0, v[188:189]
	s_mov_b32 m0, s59
	s_nop 0
	global_load_lds_dwordx4 v[228:229], off
	s_mov_b32 m0, s60
	s_nop 0
	global_load_lds_dwordx4 v[230:231], off
	s_waitcnt vmcnt(8)
	s_waitcnt lgkmcnt(0)
	s_barrier
; #define PG8_STAGE(bufoff, gbase, voff) do { _Pragma("unroll") for (int _i = 0; _i < 2; ++_i) \
;         __builtin_amdgcn_global_load_lds((const unsigned*)((const char*)(gbase) + (voff)[_i]), (PG8_LAS unsigned*)(lds + (bufoff) + ldsw + _i * 8192), 16, 0, 0); } while (0)
; #define PG8_LDA(dst, b, h) do { _Pragma("unroll") for (int m = 0; m < 4; ++m) _Pragma("unroll") for (int k = 0; k < 2; ++k) dst[m][k] = *(const PG8_LAS bf16x8*)(lds + PG8_SA(b, h) + aoff + m * 2048 + k * 1024); } while (0)
; #define PG8_LDB(dst, b, h) do { _Pragma("unroll") for (int n = 0; n < 2; ++n) _Pragma("unroll") for (int k = 0; k < 2; ++k) dst[n][k] = *(const PG8_LAS bf16x8*)(lds + PG8_SB(b, h) + boff + n * 2048 + k * 1024); } while (0)
; #define PG8_MMA(ai, bj, At, Bt) do { __builtin_amdgcn_s_setprio(1); _Pragma("unroll") for (int m = 0; m < 4; ++m) _Pragma("unroll") for (int n = 0; n < 2; ++n) _Pragma("unroll") for (int k = 0; k < 2; ++k) \
;         acc[ai][bj][m][n] = __builtin_amdgcn_mfma_f32_16x16x32_bf16(Bt[n][k], At[m][k], acc[ai][bj][m][n], 0, 0, 0); __builtin_amdgcn_s_setprio(0); } while (0)
; #define PG8_WAIT_V(n) asm volatile("s_waitcnt vmcnt(" #n ")" ::: "memory")
; #define PG8_WAIT_L(n) asm volatile("s_waitcnt lgkmcnt(" #n ")" ::: "memory")
; #define PG8_BAR __builtin_amdgcn_s_barrier()
; #define PG8_SCHED __builtin_amdgcn_sched_barrier(0)
; template <class Epi, class Sched, bool ALIGN_EPI = false, bool SP2 = false>
; __device__ __forceinline__ void gemm_phase(PG8_LAS unsigned char* lds, const int Kdim, const Sched& S, const Epi& E) {
;     ...
;             PG8_WAIT_V(8); PG8_WAIT_L(0); PG8_BAR; PG8_MMA(1, 0, At, B0); PG8_MMA(1, 1, At, B1); PG8_BAR; PG8_SCHED;
;             PG8_LDB(B0, 1, 0); PG8_LDB(B1, 1, 1); PG8_SCHED; PG8_LDA(At, 1, 0); PG8_STAGE(PG8_SA(0, 1), a2 + hstep, voffA);
;             PG8_WAIT_V(8); PG8_WAIT_L(0); PG8_BAR; PG8_MMA(0, 0, At, B0); PG8_MMA(0, 1, At, B1); PG8_BAR; PG8_SCHED;
	s_setprio 1
	s_waitcnt lgkmcnt(0)
	v_mfma_f32_16x16x32_bf16 v[60:63], v[140:143], v[180:183], 0
	v_mfma_f32_16x16x32_bf16 v[56:59], v[156:159], v[180:183], 0
	v_mfma_f32_16x16x32_bf16 v[44:47], v[140:143], v[194:197], 0
	v_mfma_f32_16x16x32_bf16 v[40:43], v[156:159], v[194:197], 0
	v_mfma_f32_16x16x32_bf16 v[28:31], v[140:143], v[212:215], 0
	v_mfma_f32_16x16x32_bf16 v[24:27], v[156:159], v[212:215], 0
	v_mfma_f32_16x16x32_bf16 v[12:15], v[140:143], v[220:223], 0
	v_mfma_f32_16x16x32_bf16 v[8:11], v[156:159], v[220:223], 0
	v_mfma_f32_16x16x32_bf16 v[60:63], v[148:151], v[184:187], v[60:63]
	v_mfma_f32_16x16x32_bf16 v[56:59], v[160:163], v[184:187], v[56:59]
	v_mfma_f32_16x16x32_bf16 v[44:47], v[148:151], v[198:201], v[44:47]
	v_mfma_f32_16x16x32_bf16 v[40:43], v[160:163], v[198:201], v[40:43]
	v_mfma_f32_16x16x32_bf16 v[28:31], v[148:151], v[216:219], v[28:31]
	v_mfma_f32_16x16x32_bf16 v[24:27], v[160:163], v[216:219], v[24:27]
	v_mfma_f32_16x16x32_bf16 v[12:15], v[148:151], v[224:227], v[12:15]
	v_mfma_f32_16x16x32_bf16 v[8:11], v[160:163], v[224:227], v[8:11]
	v_mfma_f32_16x16x32_bf16 v[52:55], v[164:167], v[180:183], 0
	v_mfma_f32_16x16x32_bf16 v[48:51], v[172:175], v[180:183], 0
	v_mfma_f32_16x16x32_bf16 v[36:39], v[164:167], v[194:197], 0
	v_mfma_f32_16x16x32_bf16 v[32:35], v[172:175], v[194:197], 0
	v_mfma_f32_16x16x32_bf16 v[20:23], v[164:167], v[212:215], 0
	v_mfma_f32_16x16x32_bf16 v[16:19], v[172:175], v[212:215], 0
	v_mfma_f32_16x16x32_bf16 v[4:7], v[164:167], v[220:223], 0
	v_mfma_f32_16x16x32_bf16 v[0:3], v[172:175], v[220:223], 0
	v_mfma_f32_16x16x32_bf16 v[52:55], v[168:171], v[184:187], v[52:55]
	v_mfma_f32_16x16x32_bf16 v[48:51], v[176:179], v[184:187], v[48:51]
	v_mfma_f32_16x16x32_bf16 v[36:39], v[168:171], v[198:201], v[36:39]
	v_mfma_f32_16x16x32_bf16 v[32:35], v[176:179], v[198:201], v[32:35]
	v_mfma_f32_16x16x32_bf16 v[20:23], v[168:171], v[216:219], v[20:23]
	v_mfma_f32_16x16x32_bf16 v[16:19], v[176:179], v[216:219], v[16:19]
	v_mfma_f32_16x16x32_bf16 v[4:7], v[168:171], v[224:227], v[4:7]
	v_mfma_f32_16x16x32_bf16 v[0:3], v[176:179], v[224:227], v[0:3]
	s_setprio 0
	s_barrier
	ds_read_b128 v[140:143], v137
	ds_read_b128 v[148:151], v137 offset:1024
	ds_read_b128 v[156:159], v137 offset:2048
	ds_read_b128 v[160:163], v137 offset:3072
	ds_read_b128 v[164:167], v138
	ds_read_b128 v[168:171], v138 offset:1024
	ds_read_b128 v[172:175], v138 offset:2048
	ds_read_b128 v[176:179], v138 offset:3072
	s_add_u32 s8, s8, 0x40000
	s_addc_u32 s9, s9, 0
	s_mov_b32 m0, s61
	v_lshl_add_u64 v[232:233], s[8:9], 0, v[188:189]
	ds_read_b128 v[180:183], v136 offset:32768
	ds_read_b128 v[184:187], v136 offset:33792
	ds_read_b128 v[194:197], v136 offset:34816
	ds_read_b128 v[198:201], v136 offset:35840
	ds_read_b128 v[212:215], v136 offset:36864
	ds_read_b128 v[216:219], v136 offset:37888
	ds_read_b128 v[220:223], v136 offset:38912
	ds_read_b128 v[224:227], v136 offset:39936
	global_load_lds_dwordx4 v[232:233], off
	v_lshl_add_u64 v[232:233], s[8:9], 0, v[132:133]
	s_mov_b32 m0, s62
	s_nop 0
	global_load_lds_dwordx4 v[232:233], off
	s_waitcnt vmcnt(8)
	s_waitcnt lgkmcnt(0)
	s_barrier
	s_setprio 1
	s_waitcnt lgkmcnt(0)
	v_mfma_f32_16x16x32_bf16 v[124:127], v[140:143], v[180:183], v[124:127]
	v_mfma_f32_16x16x32_bf16 v[120:123], v[156:159], v[180:183], v[120:123]
	v_mfma_f32_16x16x32_bf16 v[108:111], v[140:143], v[194:197], v[108:111]
	v_mfma_f32_16x16x32_bf16 v[104:107], v[156:159], v[194:197], v[104:107]
	v_mfma_f32_16x16x32_bf16 v[92:95], v[140:143], v[212:215], v[92:95]
	v_mfma_f32_16x16x32_bf16 v[88:91], v[156:159], v[212:215], v[88:91]
	v_mfma_f32_16x16x32_bf16 v[76:79], v[140:143], v[220:223], v[76:79]
	v_mfma_f32_16x16x32_bf16 v[72:75], v[156:159], v[220:223], v[72:75]
	v_mfma_f32_16x16x32_bf16 v[124:127], v[148:151], v[184:187], v[124:127]
	v_mfma_f32_16x16x32_bf16 v[120:123], v[160:163], v[184:187], v[120:123]
	v_mfma_f32_16x16x32_bf16 v[108:111], v[148:151], v[198:201], v[108:111]
	v_mfma_f32_16x16x32_bf16 v[104:107], v[160:163], v[198:201], v[104:107]
	v_mfma_f32_16x16x32_bf16 v[92:95], v[148:151], v[216:219], v[92:95]
	v_mfma_f32_16x16x32_bf16 v[88:91], v[160:163], v[216:219], v[88:91]
	v_mfma_f32_16x16x32_bf16 v[76:79], v[148:151], v[224:227], v[76:79]
	v_mfma_f32_16x16x32_bf16 v[72:75], v[160:163], v[224:227], v[72:75]
	v_mfma_f32_16x16x32_bf16 v[116:119], v[164:167], v[180:183], v[116:119]
	v_mfma_f32_16x16x32_bf16 v[112:115], v[172:175], v[180:183], v[112:115]
	v_mfma_f32_16x16x32_bf16 v[100:103], v[164:167], v[194:197], v[100:103]
	v_mfma_f32_16x16x32_bf16 v[96:99], v[172:175], v[194:197], v[96:99]
	v_mfma_f32_16x16x32_bf16 v[84:87], v[164:167], v[212:215], v[84:87]
	v_mfma_f32_16x16x32_bf16 v[80:83], v[172:175], v[212:215], v[80:83]
	v_mfma_f32_16x16x32_bf16 v[68:71], v[164:167], v[220:223], v[68:71]
	v_mfma_f32_16x16x32_bf16 v[64:67], v[172:175], v[220:223], v[64:67]
	v_mfma_f32_16x16x32_bf16 v[116:119], v[168:171], v[184:187], v[116:119]
	v_mfma_f32_16x16x32_bf16 v[112:115], v[176:179], v[184:187], v[112:115]
	v_mfma_f32_16x16x32_bf16 v[100:103], v[168:171], v[198:201], v[100:103]
	v_mfma_f32_16x16x32_bf16 v[96:99], v[176:179], v[198:201], v[96:99]
	v_mfma_f32_16x16x32_bf16 v[84:87], v[168:171], v[216:219], v[84:87]
	v_mfma_f32_16x16x32_bf16 v[80:83], v[176:179], v[216:219], v[80:83]
	v_mfma_f32_16x16x32_bf16 v[68:71], v[168:171], v[224:227], v[68:71]
	v_mfma_f32_16x16x32_bf16 v[64:67], v[176:179], v[224:227], v[64:67]
	s_setprio 0
	s_barrier
; #define PG8_STAGE(bufoff, gbase, voff) do { _Pragma("unroll") for (int _i = 0; _i < 2; ++_i) \
;         __builtin_amdgcn_global_load_lds((const unsigned*)((const char*)(gbase) + (voff)[_i]), (PG8_LAS unsigned*)(lds + (bufoff) + ldsw + _i * 8192), 16, 0, 0); } while (0)
; #define PG8_LDA(dst, b, h) do { _Pragma("unroll") for (int m = 0; m < 4; ++m) _Pragma("unroll") for (int k = 0; k < 2; ++k) dst[m][k] = *(const PG8_LAS bf16x8*)(lds + PG8_SA(b, h) + aoff + m * 2048 + k * 1024); } while (0)
; #define PG8_MMA(ai, bj, At, Bt) do { __builtin_amdgcn_s_setprio(1); _Pragma("unroll") for (int m = 0; m < 4; ++m) _Pragma("unroll") for (int n = 0; n < 2; ++n) _Pragma("unroll") for (int k = 0; k < 2; ++k) \
;         acc[ai][bj][m][n] = __builtin_amdgcn_mfma_f32_16x16x32_bf16(Bt[n][k], At[m][k], acc[ai][bj][m][n], 0, 0, 0); __builtin_amdgcn_s_setprio(0); } while (0)
; #define PG8_WAIT_V(n) asm volatile("s_waitcnt vmcnt(" #n ")" ::: "memory")
; #define PG8_WAIT_L(n) asm volatile("s_waitcnt lgkmcnt(" #n ")" ::: "memory")
; #define PG8_BAR __builtin_amdgcn_s_barrier()
; #define PG8_SCHED __builtin_amdgcn_sched_barrier(0)
; template <class Epi, class Sched, bool ALIGN_EPI = false, bool SP2 = false>
; __device__ __forceinline__ void gemm_phase(PG8_LAS unsigned char* lds, const int Kdim, const Sched& S, const Epi& E) {
;     ...
;             PG8_LDA(At, 1, 1); PG8_STAGE(PG8_SB(1, 0), b3, voffB); PG8_STAGE(PG8_SB(1, 1), b3 + hstep, voffB); PG8_STAGE(PG8_SA(1, 0), a3, voffA);
;             PG8_WAIT_V(8); PG8_WAIT_L(0); PG8_BAR; PG8_MMA(1, 0, At, B0); PG8_MMA(1, 1, At, B1); PG8_BAR; PG8_SCHED;
	s_mov_b32 m0, s68
	v_lshl_add_u64 v[144:145], v[144:145], 0, s[86:87]
	s_add_u32 s6, s6, 0x40080
	ds_read_b128 v[180:183], v136 offset:49152
	ds_read_b128 v[184:187], v136 offset:50176
	ds_read_b128 v[194:197], v136 offset:51200
	ds_read_b128 v[198:201], v136 offset:52224
	ds_read_b128 v[212:215], v136 offset:53248
	ds_read_b128 v[216:219], v136 offset:54272
	ds_read_b128 v[220:223], v136 offset:55296
	ds_read_b128 v[224:227], v136 offset:56320
	global_load_lds_dwordx4 v[144:145], off
	v_lshl_add_u64 v[144:145], v[202:203], 0, s[86:87]
	s_mov_b32 m0, s69
	s_addc_u32 s7, s7, 0
	global_load_lds_dwordx4 v[144:145], off
	v_lshl_add_u64 v[144:145], s[6:7], 0, v[128:129]
	s_mov_b32 m0, s73
	s_nop 0
	global_load_lds_dwordx4 v[144:145], off
	v_lshl_add_u64 v[144:145], s[6:7], 0, v[130:131]
	s_mov_b32 m0, s77
	s_nop 0
	global_load_lds_dwordx4 v[144:145], off
	v_lshl_add_u64 v[144:145], v[228:229], 0, s[86:87]
	s_mov_b32 m0, s70
	s_nop 0
	global_load_lds_dwordx4 v[144:145], off
	v_lshl_add_u64 v[144:145], v[230:231], 0, s[86:87]
	s_mov_b32 m0, s71
	s_nop 0
	global_load_lds_dwordx4 v[144:145], off
	s_waitcnt vmcnt(8)
	s_waitcnt lgkmcnt(0)
	s_barrier
	s_setprio 1
	s_waitcnt lgkmcnt(0)
	v_mfma_f32_16x16x32_bf16 v[60:63], v[140:143], v[180:183], v[60:63]
	v_mfma_f32_16x16x32_bf16 v[56:59], v[156:159], v[180:183], v[56:59]
	v_mfma_f32_16x16x32_bf16 v[44:47], v[140:143], v[194:197], v[44:47]
	v_mfma_f32_16x16x32_bf16 v[40:43], v[156:159], v[194:197], v[40:43]
	v_mfma_f32_16x16x32_bf16 v[28:31], v[140:143], v[212:215], v[28:31]
	v_mfma_f32_16x16x32_bf16 v[24:27], v[156:159], v[212:215], v[24:27]
	v_mfma_f32_16x16x32_bf16 v[12:15], v[140:143], v[220:223], v[12:15]
	v_mfma_f32_16x16x32_bf16 v[8:11], v[156:159], v[220:223], v[8:11]
	v_mfma_f32_16x16x32_bf16 v[60:63], v[148:151], v[184:187], v[60:63]
	v_mfma_f32_16x16x32_bf16 v[56:59], v[160:163], v[184:187], v[56:59]
	v_mfma_f32_16x16x32_bf16 v[44:47], v[148:151], v[198:201], v[44:47]
	v_mfma_f32_16x16x32_bf16 v[40:43], v[160:163], v[198:201], v[40:43]
	v_mfma_f32_16x16x32_bf16 v[28:31], v[148:151], v[216:219], v[28:31]
	v_mfma_f32_16x16x32_bf16 v[24:27], v[160:163], v[216:219], v[24:27]
	v_mfma_f32_16x16x32_bf16 v[12:15], v[148:151], v[224:227], v[12:15]
	v_mfma_f32_16x16x32_bf16 v[8:11], v[160:163], v[224:227], v[8:11]
	v_mfma_f32_16x16x32_bf16 v[52:55], v[164:167], v[180:183], v[52:55]
	v_mfma_f32_16x16x32_bf16 v[48:51], v[172:175], v[180:183], v[48:51]
	v_mfma_f32_16x16x32_bf16 v[36:39], v[164:167], v[194:197], v[36:39]
	v_mfma_f32_16x16x32_bf16 v[32:35], v[172:175], v[194:197], v[32:35]
	v_mfma_f32_16x16x32_bf16 v[20:23], v[164:167], v[212:215], v[20:23]
	v_mfma_f32_16x16x32_bf16 v[16:19], v[172:175], v[212:215], v[16:19]
	v_mfma_f32_16x16x32_bf16 v[4:7], v[164:167], v[220:223], v[4:7]
	v_mfma_f32_16x16x32_bf16 v[0:3], v[172:175], v[220:223], v[0:3]
	v_mfma_f32_16x16x32_bf16 v[52:55], v[168:171], v[184:187], v[52:55]
	v_mfma_f32_16x16x32_bf16 v[48:51], v[176:179], v[184:187], v[48:51]
	v_mfma_f32_16x16x32_bf16 v[36:39], v[168:171], v[198:201], v[36:39]
	v_mfma_f32_16x16x32_bf16 v[32:35], v[176:179], v[198:201], v[32:35]
	v_mfma_f32_16x16x32_bf16 v[20:23], v[168:171], v[216:219], v[20:23]
	v_mfma_f32_16x16x32_bf16 v[16:19], v[176:179], v[216:219], v[16:19]
	v_mfma_f32_16x16x32_bf16 v[4:7], v[168:171], v[224:227], v[4:7]
	v_mfma_f32_16x16x32_bf16 v[0:3], v[176:179], v[224:227], v[0:3]
	s_setprio 0
	s_barrier
	s_add_i32 s34, s34, 2
	s_add_u32 s4, s4, 0x100
	s_addc_u32 s5, s5, 0
	s_add_u32 s25, s25, 0x100
	s_addc_u32 s29, s29, 0

; #define PG8_STAGE(bufoff, gbase, voff) do { _Pragma("unroll") for (int _i = 0; _i < 2; ++_i) \
;         __builtin_amdgcn_global_load_lds((const unsigned*)((const char*)(gbase) + (voff)[_i]), (PG8_LAS unsigned*)(lds + (bufoff) + ldsw + _i * 8192), 16, 0, 0); } while (0)
; #define PG8_LDA(dst, b, h) do { _Pragma("unroll") for (int m = 0; m < 4; ++m) _Pragma("unroll") for (int k = 0; k < 2; ++k) dst[m][k] = *(const PG8_LAS bf16x8*)(lds + PG8_SA(b, h) + aoff + m * 2048 + k * 1024); } while (0)
; #define PG8_LDB(dst, b, h) do { _Pragma("unroll") for (int n = 0; n < 2; ++n) _Pragma("unroll") for (int k = 0; k < 2; ++k) dst[n][k] = *(const PG8_LAS bf16x8*)(lds + PG8_SB(b, h) + boff + n * 2048 + k * 1024); } while (0)
; #define PG8_MMA(ai, bj, At, Bt) do { __builtin_amdgcn_s_setprio(1); _Pragma("unroll") for (int m = 0; m < 4; ++m) _Pragma("unroll") for (int n = 0; n < 2; ++n) _Pragma("unroll") for (int k = 0; k < 2; ++k) \
;         acc[ai][bj][m][n] = __builtin_amdgcn_mfma_f32_16x16x32_bf16(Bt[n][k], At[m][k], acc[ai][bj][m][n], 0, 0, 0); __builtin_amdgcn_s_setprio(0); } while (0)
; #define PG8_WAIT_V(n) asm volatile("s_waitcnt vmcnt(" #n ")" ::: "memory")
; #define PG8_WAIT_L(n) asm volatile("s_waitcnt lgkmcnt(" #n ")" ::: "memory")
; template <class Epi, class Sched, bool ALIGN_EPI = false, bool SP2 = false>
; __device__ __forceinline__ void gemm_phase(PG8_LAS unsigned char* lds, const int Kdim, const Sched& S, const Epi& E) {
;     ...
;         for (int t = 0; t < nt; t += 2) {
;             const bool last = (t == nt - 2);
;             const char* a1 = cA + (size_t)(t + 1) * kstep;
;             const char* a2 = last ? nA : cA + (size_t)(t + 2) * kstep; const char* b2 = last ? nB : cB + (size_t)(t + 2) * kstep;
;             const char* a3 = a2 + kstep; const char* b3 = b2 + kstep;
;             if constexpr (SP2) {
;             PG8_LDB(B0, 0, 0); PG8_LDB(B1, 0, 1); PG8_SCHED; PG8_LDA(At, 0, 0); PG8_STAGE(PG8_SA(1, 1), a1 + hstep, voffA);
;             PG8_WAIT_V(8); PG8_WAIT_L(0); PG8_BAR; PG8_MMA(0, 0, At, B0); PG8_MMA(0, 1, At, B1); PG8_BAR; PG8_SCHED;
;             PG8_LDA(At, 0, 1); PG8_STAGE(PG8_SB(0, 0), b2, voffB); PG8_STAGE(PG8_SB(0, 1), b2 + hstep, voffB); PG8_STAGE(PG8_SA(0, 0), a2, voffA);
;             PG8_WAIT_V(8); PG8_WAIT_L(0); PG8_BAR; PG8_MMA(1, 0, At, B0); PG8_MMA(1, 1, At, B1); PG8_BAR; PG8_SCHED;
.LBB0_642:
	s_and_b64 s[0:1], s[22:23], exec
	s_cselect_b32 s0, s19, s5
	s_cselect_b32 s1, s18, s4
	s_cselect_b32 s3, s21, s25
	s_cselect_b32 s15, s20, s24
	s_add_u32 s4, s4, 0x40080
	s_addc_u32 s5, s5, 0
	v_add_u32_e32 v2, s52, v0
	s_add_u32 s17, s24, 0x100
	s_waitcnt lgkmcnt(0)
	v_add_u32_e32 v134, s54, v1
	v_mov_b32_e32 v133, v189
	v_mov_b32_e32 v129, v189
	v_mov_b32_e32 v131, v189
	s_addc_u32 s28, s25, 0
	s_mov_b32 s29, -2
	v_add_u32_e32 v135, s35, v2
	s_waitcnt vmcnt(0)
	v_add_u32_e32 v143, s41, v134
	ds_read_b128 v[136:139], v143
	ds_read_b128 v[144:147], v143 offset:1024
	ds_read_b128 v[148:151], v143 offset:2048
	ds_read_b128 v[152:155], v143 offset:3072
	v_add_u32_e32 v143, s44, v134
	ds_read_b128 v[156:159], v143
	ds_read_b128 v[160:163], v143 offset:1024
	ds_read_b128 v[164:167], v143 offset:2048
	ds_read_b128 v[168:171], v143 offset:3072
	s_add_u32 s24, s4, 0xfffc0080
	s_addc_u32 s25, s5, -1
	s_cmp_eq_u32 s29, 12
	s_cselect_b32 s27, s0, s25
	s_cselect_b32 s26, s1, s24
	s_cselect_b32 s25, s3, s28
	s_cselect_b32 s24, s15, s17
	v_lshl_add_u64 v[202:203], s[4:5], 0, v[188:189]
	s_add_i32 m0, s47, 0xc000
	ds_read_b128 v[172:175], v135
	ds_read_b128 v[176:179], v135 offset:1024
	ds_read_b128 v[180:183], v135 offset:2048
	ds_read_b128 v[184:187], v135 offset:3072
	ds_read_b128 v[194:197], v135 offset:4096
	ds_read_b128 v[198:201], v135 offset:5120
	ds_read_b128 v[212:215], v135 offset:6144
	ds_read_b128 v[216:219], v135 offset:7168
	global_load_lds_dwordx4 v[202:203], off
	v_lshl_add_u64 v[202:203], s[4:5], 0, v[132:133]
	s_add_i32 m0, s47, 0xe000
	s_nop 0
	global_load_lds_dwordx4 v[202:203], off
	s_waitcnt vmcnt(8)
	s_waitcnt lgkmcnt(0)
	s_barrier
	s_setprio 1
	s_waitcnt lgkmcnt(0)
	v_mfma_f32_16x16x32_bf16 v[124:127], v[136:139], v[172:175], 0
	v_mfma_f32_16x16x32_bf16 v[120:123], v[148:151], v[172:175], 0
	v_mfma_f32_16x16x32_bf16 v[108:111], v[136:139], v[180:183], 0
	v_mfma_f32_16x16x32_bf16 v[104:107], v[148:151], v[180:183], 0
	v_mfma_f32_16x16x32_bf16 v[92:95], v[136:139], v[194:197], 0
	v_mfma_f32_16x16x32_bf16 v[88:91], v[148:151], v[194:197], 0
	v_mfma_f32_16x16x32_bf16 v[76:79], v[136:139], v[212:215], 0
	v_mfma_f32_16x16x32_bf16 v[72:75], v[148:151], v[212:215], 0
	v_mfma_f32_16x16x32_bf16 v[124:127], v[144:147], v[176:179], v[124:127]
	v_mfma_f32_16x16x32_bf16 v[120:123], v[152:155], v[176:179], v[120:123]
	v_mfma_f32_16x16x32_bf16 v[108:111], v[144:147], v[184:187], v[108:111]
	v_mfma_f32_16x16x32_bf16 v[104:107], v[152:155], v[184:187], v[104:107]
	v_mfma_f32_16x16x32_bf16 v[92:95], v[144:147], v[198:201], v[92:95]
	v_mfma_f32_16x16x32_bf16 v[88:91], v[152:155], v[198:201], v[88:91]
	v_mfma_f32_16x16x32_bf16 v[76:79], v[144:147], v[216:219], v[76:79]
	v_mfma_f32_16x16x32_bf16 v[72:75], v[152:155], v[216:219], v[72:75]
	v_mfma_f32_16x16x32_bf16 v[116:119], v[156:159], v[172:175], 0
	v_mfma_f32_16x16x32_bf16 v[112:115], v[164:167], v[172:175], 0
	v_mfma_f32_16x16x32_bf16 v[100:103], v[156:159], v[180:183], 0
	v_mfma_f32_16x16x32_bf16 v[96:99], v[164:167], v[180:183], 0
	v_mfma_f32_16x16x32_bf16 v[84:87], v[156:159], v[194:197], 0
	v_mfma_f32_16x16x32_bf16 v[80:83], v[164:167], v[194:197], 0
	v_mfma_f32_16x16x32_bf16 v[68:71], v[156:159], v[212:215], 0
	v_mfma_f32_16x16x32_bf16 v[64:67], v[164:167], v[212:215], 0
	v_mfma_f32_16x16x32_bf16 v[116:119], v[160:163], v[176:179], v[116:119]
	v_mfma_f32_16x16x32_bf16 v[112:115], v[168:171], v[176:179], v[112:115]
	v_mfma_f32_16x16x32_bf16 v[100:103], v[160:163], v[184:187], v[100:103]
	v_mfma_f32_16x16x32_bf16 v[96:99], v[168:171], v[184:187], v[96:99]
	v_mfma_f32_16x16x32_bf16 v[84:87], v[160:163], v[198:201], v[84:87]
	v_mfma_f32_16x16x32_bf16 v[80:83], v[168:171], v[198:201], v[80:83]
	v_mfma_f32_16x16x32_bf16 v[68:71], v[160:163], v[216:219], v[68:71]
	v_mfma_f32_16x16x32_bf16 v[64:67], v[168:171], v[216:219], v[64:67]
	s_setprio 0
	s_barrier
	s_mov_b32 m0, s42
	v_lshl_add_u64 v[202:203], s[24:25], 0, v[128:129]
	s_add_u32 s30, s24, 0x40000
	ds_read_b128 v[172:175], v135 offset:16384
	ds_read_b128 v[176:179], v135 offset:17408
	ds_read_b128 v[180:183], v135 offset:18432
	ds_read_b128 v[184:187], v135 offset:19456
	ds_read_b128 v[194:197], v135 offset:20480
	ds_read_b128 v[198:201], v135 offset:21504
	ds_read_b128 v[212:215], v135 offset:22528
	ds_read_b128 v[216:219], v135 offset:23552
	global_load_lds_dwordx4 v[202:203], off
	v_lshl_add_u64 v[204:205], s[24:25], 0, v[130:131]
	s_mov_b32 m0, s43
	s_addc_u32 s31, s25, 0
	global_load_lds_dwordx4 v[204:205], off
	v_lshl_add_u64 v[220:221], s[30:31], 0, v[128:129]
	s_mov_b32 m0, s45
	v_lshl_add_u64 v[222:223], s[26:27], 0, v[132:133]
	global_load_lds_dwordx4 v[220:221], off
	v_lshl_add_u64 v[220:221], s[30:31], 0, v[130:131]
	s_mov_b32 m0, s46
	s_nop 0
	global_load_lds_dwordx4 v[220:221], off
	v_lshl_add_u64 v[220:221], s[26:27], 0, v[188:189]
	s_mov_b32 m0, s47
	s_nop 0
	global_load_lds_dwordx4 v[220:221], off
	s_mov_b32 m0, s48
	s_nop 0
	global_load_lds_dwordx4 v[222:223], off
	s_waitcnt vmcnt(8)
	s_waitcnt lgkmcnt(0)
	s_barrier
; #define PG8_STAGE(bufoff, gbase, voff) do { _Pragma("unroll") for (int _i = 0; _i < 2; ++_i) \
;         __builtin_amdgcn_global_load_lds((const unsigned*)((const char*)(gbase) + (voff)[_i]), (PG8_LAS unsigned*)(lds + (bufoff) + ldsw + _i * 8192), 16, 0, 0); } while (0)
; #define PG8_LDA(dst, b, h) do { _Pragma("unroll") for (int m = 0; m < 4; ++m) _Pragma("unroll") for (int k = 0; k < 2; ++k) dst[m][k] = *(const PG8_LAS bf16x8*)(lds + PG8_SA(b, h) + aoff + m * 2048 + k * 1024); } while (0)
; #define PG8_LDB(dst, b, h) do { _Pragma("unroll") for (int n = 0; n < 2; ++n) _Pragma("unroll") for (int k = 0; k < 2; ++k) dst[n][k] = *(const PG8_LAS bf16x8*)(lds + PG8_SB(b, h) + boff + n * 2048 + k * 1024); } while (0)
; #define PG8_MMA(ai, bj, At, Bt) do { __builtin_amdgcn_s_setprio(1); _Pragma("unroll") for (int m = 0; m < 4; ++m) _Pragma("unroll") for (int n = 0; n < 2; ++n) _Pragma("unroll") for (int k = 0; k < 2; ++k) \
;         acc[ai][bj][m][n] = __builtin_amdgcn_mfma_f32_16x16x32_bf16(Bt[n][k], At[m][k], acc[ai][bj][m][n], 0, 0, 0); __builtin_amdgcn_s_setprio(0); } while (0)
; #define PG8_WAIT_V(n) asm volatile("s_waitcnt vmcnt(" #n ")" ::: "memory")
; #define PG8_WAIT_L(n) asm volatile("s_waitcnt lgkmcnt(" #n ")" ::: "memory")
; #define PG8_BAR __builtin_amdgcn_s_barrier()
; #define PG8_SCHED __builtin_amdgcn_sched_barrier(0)
; template <class Epi, class Sched, bool ALIGN_EPI = false, bool SP2 = false>
; __device__ __forceinline__ void gemm_phase(PG8_LAS unsigned char* lds, const int Kdim, const Sched& S, const Epi& E) {
;     ...
;             PG8_WAIT_V(8); PG8_WAIT_L(0); PG8_BAR; PG8_MMA(1, 0, At, B0); PG8_MMA(1, 1, At, B1); PG8_BAR; PG8_SCHED;
;             PG8_LDB(B0, 1, 0); PG8_LDB(B1, 1, 1); PG8_SCHED; PG8_LDA(At, 1, 0); PG8_STAGE(PG8_SA(0, 1), a2 + hstep, voffA);
;             PG8_WAIT_V(8); PG8_WAIT_L(0); PG8_BAR; PG8_MMA(0, 0, At, B0); PG8_MMA(0, 1, At, B1); PG8_BAR; PG8_SCHED;
	s_setprio 1
	s_waitcnt lgkmcnt(0)
	v_mfma_f32_16x16x32_bf16 v[60:63], v[136:139], v[172:175], 0
	v_mfma_f32_16x16x32_bf16 v[56:59], v[148:151], v[172:175], 0
	v_mfma_f32_16x16x32_bf16 v[44:47], v[136:139], v[180:183], 0
	v_mfma_f32_16x16x32_bf16 v[40:43], v[148:151], v[180:183], 0
	v_mfma_f32_16x16x32_bf16 v[28:31], v[136:139], v[194:197], 0
	v_mfma_f32_16x16x32_bf16 v[24:27], v[148:151], v[194:197], 0
	v_mfma_f32_16x16x32_bf16 v[12:15], v[136:139], v[212:215], 0
	v_mfma_f32_16x16x32_bf16 v[8:11], v[148:151], v[212:215], 0
	v_mfma_f32_16x16x32_bf16 v[60:63], v[144:147], v[176:179], v[60:63]
	v_mfma_f32_16x16x32_bf16 v[56:59], v[152:155], v[176:179], v[56:59]
	v_mfma_f32_16x16x32_bf16 v[44:47], v[144:147], v[184:187], v[44:47]
	v_mfma_f32_16x16x32_bf16 v[40:43], v[152:155], v[184:187], v[40:43]
	v_mfma_f32_16x16x32_bf16 v[28:31], v[144:147], v[198:201], v[28:31]
	v_mfma_f32_16x16x32_bf16 v[24:27], v[152:155], v[198:201], v[24:27]
	v_mfma_f32_16x16x32_bf16 v[12:15], v[144:147], v[216:219], v[12:15]
	v_mfma_f32_16x16x32_bf16 v[8:11], v[152:155], v[216:219], v[8:11]
	v_mfma_f32_16x16x32_bf16 v[52:55], v[156:159], v[172:175], 0
	v_mfma_f32_16x16x32_bf16 v[48:51], v[164:167], v[172:175], 0
	v_mfma_f32_16x16x32_bf16 v[36:39], v[156:159], v[180:183], 0
	v_mfma_f32_16x16x32_bf16 v[32:35], v[164:167], v[180:183], 0
	v_mfma_f32_16x16x32_bf16 v[20:23], v[156:159], v[194:197], 0
	v_mfma_f32_16x16x32_bf16 v[16:19], v[164:167], v[194:197], 0
	v_mfma_f32_16x16x32_bf16 v[4:7], v[156:159], v[212:215], 0
	v_mfma_f32_16x16x32_bf16 v[0:3], v[164:167], v[212:215], 0
	v_mfma_f32_16x16x32_bf16 v[52:55], v[160:163], v[176:179], v[52:55]
	v_mfma_f32_16x16x32_bf16 v[48:51], v[168:171], v[176:179], v[48:51]
	v_mfma_f32_16x16x32_bf16 v[36:39], v[160:163], v[184:187], v[36:39]
	v_mfma_f32_16x16x32_bf16 v[32:35], v[168:171], v[184:187], v[32:35]
	v_mfma_f32_16x16x32_bf16 v[20:23], v[160:163], v[198:201], v[20:23]
	v_mfma_f32_16x16x32_bf16 v[16:19], v[168:171], v[198:201], v[16:19]
	v_mfma_f32_16x16x32_bf16 v[4:7], v[160:163], v[216:219], v[4:7]
	v_mfma_f32_16x16x32_bf16 v[0:3], v[168:171], v[216:219], v[0:3]
	s_setprio 0
	s_barrier
	v_add_u32_e32 v143, s55, v134
	ds_read_b128 v[136:139], v143
	ds_read_b128 v[144:147], v143 offset:1024
	ds_read_b128 v[148:151], v143 offset:2048
	ds_read_b128 v[152:155], v143 offset:3072
	v_add_u32_e32 v143, s60, v134
	ds_read_b128 v[156:159], v143
	ds_read_b128 v[160:163], v143 offset:1024
	ds_read_b128 v[164:167], v143 offset:2048
	ds_read_b128 v[168:171], v143 offset:3072
	s_add_u32 s26, s26, 0x40000
	s_addc_u32 s27, s27, 0
	s_mov_b32 m0, s49
	v_lshl_add_u64 v[224:225], s[26:27], 0, v[188:189]
	ds_read_b128 v[172:175], v135 offset:32768
	ds_read_b128 v[176:179], v135 offset:33792
	ds_read_b128 v[180:183], v135 offset:34816
	ds_read_b128 v[184:187], v135 offset:35840
	ds_read_b128 v[194:197], v135 offset:36864
	ds_read_b128 v[198:201], v135 offset:37888
	ds_read_b128 v[212:215], v135 offset:38912
	ds_read_b128 v[216:219], v135 offset:39936
	global_load_lds_dwordx4 v[224:225], off
	v_lshl_add_u64 v[224:225], s[26:27], 0, v[132:133]
	s_mov_b32 m0, s50
	s_nop 0
	global_load_lds_dwordx4 v[224:225], off
	s_waitcnt vmcnt(8)
	s_waitcnt lgkmcnt(0)
	s_barrier
	s_setprio 1
	s_waitcnt lgkmcnt(0)
	v_mfma_f32_16x16x32_bf16 v[124:127], v[136:139], v[172:175], v[124:127]
	v_mfma_f32_16x16x32_bf16 v[120:123], v[148:151], v[172:175], v[120:123]
	v_mfma_f32_16x16x32_bf16 v[108:111], v[136:139], v[180:183], v[108:111]
	v_mfma_f32_16x16x32_bf16 v[104:107], v[148:151], v[180:183], v[104:107]
	v_mfma_f32_16x16x32_bf16 v[92:95], v[136:139], v[194:197], v[92:95]
	v_mfma_f32_16x16x32_bf16 v[88:91], v[148:151], v[194:197], v[88:91]
	v_mfma_f32_16x16x32_bf16 v[76:79], v[136:139], v[212:215], v[76:79]
	v_mfma_f32_16x16x32_bf16 v[72:75], v[148:151], v[212:215], v[72:75]
	v_mfma_f32_16x16x32_bf16 v[124:127], v[144:147], v[176:179], v[124:127]
	v_mfma_f32_16x16x32_bf16 v[120:123], v[152:155], v[176:179], v[120:123]
	v_mfma_f32_16x16x32_bf16 v[108:111], v[144:147], v[184:187], v[108:111]
	v_mfma_f32_16x16x32_bf16 v[104:107], v[152:155], v[184:187], v[104:107]
	v_mfma_f32_16x16x32_bf16 v[92:95], v[144:147], v[198:201], v[92:95]
	v_mfma_f32_16x16x32_bf16 v[88:91], v[152:155], v[198:201], v[88:91]
	v_mfma_f32_16x16x32_bf16 v[76:79], v[144:147], v[216:219], v[76:79]
	v_mfma_f32_16x16x32_bf16 v[72:75], v[152:155], v[216:219], v[72:75]
	v_mfma_f32_16x16x32_bf16 v[116:119], v[156:159], v[172:175], v[116:119]
	v_mfma_f32_16x16x32_bf16 v[112:115], v[164:167], v[172:175], v[112:115]
	v_mfma_f32_16x16x32_bf16 v[100:103], v[156:159], v[180:183], v[100:103]
	v_mfma_f32_16x16x32_bf16 v[96:99], v[164:167], v[180:183], v[96:99]
	v_mfma_f32_16x16x32_bf16 v[84:87], v[156:159], v[194:197], v[84:87]
	v_mfma_f32_16x16x32_bf16 v[80:83], v[164:167], v[194:197], v[80:83]
	v_mfma_f32_16x16x32_bf16 v[68:71], v[156:159], v[212:215], v[68:71]
	v_mfma_f32_16x16x32_bf16 v[64:67], v[164:167], v[212:215], v[64:67]
	v_mfma_f32_16x16x32_bf16 v[116:119], v[160:163], v[176:179], v[116:119]
	v_mfma_f32_16x16x32_bf16 v[112:115], v[168:171], v[176:179], v[112:115]
	v_mfma_f32_16x16x32_bf16 v[100:103], v[160:163], v[184:187], v[100:103]
	v_mfma_f32_16x16x32_bf16 v[96:99], v[168:171], v[184:187], v[96:99]
	v_mfma_f32_16x16x32_bf16 v[84:87], v[160:163], v[198:201], v[84:87]
	v_mfma_f32_16x16x32_bf16 v[80:83], v[168:171], v[198:201], v[80:83]
	v_mfma_f32_16x16x32_bf16 v[68:71], v[160:163], v[216:219], v[68:71]
	v_mfma_f32_16x16x32_bf16 v[64:67], v[168:171], v[216:219], v[64:67]
	s_setprio 0
	s_barrier
; #define PG8_STAGE(bufoff, gbase, voff) do { _Pragma("unroll") for (int _i = 0; _i < 2; ++_i) \
;         __builtin_amdgcn_global_load_lds((const unsigned*)((const char*)(gbase) + (voff)[_i]), (PG8_LAS unsigned*)(lds + (bufoff) + ldsw + _i * 8192), 16, 0, 0); } while (0)
; #define PG8_LDA(dst, b, h) do { _Pragma("unroll") for (int m = 0; m < 4; ++m) _Pragma("unroll") for (int k = 0; k < 2; ++k) dst[m][k] = *(const PG8_LAS bf16x8*)(lds + PG8_SA(b, h) + aoff + m * 2048 + k * 1024); } while (0)
; #define PG8_MMA(ai, bj, At, Bt) do { __builtin_amdgcn_s_setprio(1); _Pragma("unroll") for (int m = 0; m < 4; ++m) _Pragma("unroll") for (int n = 0; n < 2; ++n) _Pragma("unroll") for (int k = 0; k < 2; ++k) \
;         acc[ai][bj][m][n] = __builtin_amdgcn_mfma_f32_16x16x32_bf16(Bt[n][k], At[m][k], acc[ai][bj][m][n], 0, 0, 0); __builtin_amdgcn_s_setprio(0); } while (0)
; #define PG8_WAIT_V(n) asm volatile("s_waitcnt vmcnt(" #n ")" ::: "memory")
; #define PG8_WAIT_L(n) asm volatile("s_waitcnt lgkmcnt(" #n ")" ::: "memory")
; #define PG8_BAR __builtin_amdgcn_s_barrier()
; #define PG8_SCHED __builtin_amdgcn_sched_barrier(0)
; template <class Epi, class Sched, bool ALIGN_EPI = false, bool SP2 = false>
; __device__ __forceinline__ void gemm_phase(PG8_LAS unsigned char* lds, const int Kdim, const Sched& S, const Epi& E) {
;     ...
;             PG8_LDA(At, 1, 1); PG8_STAGE(PG8_SB(1, 0), b3, voffB); PG8_STAGE(PG8_SB(1, 1), b3 + hstep, voffB); PG8_STAGE(PG8_SA(1, 0), a3, voffA);
;             PG8_WAIT_V(8); PG8_WAIT_L(0); PG8_BAR; PG8_MMA(1, 0, At, B0); PG8_MMA(1, 1, At, B1); PG8_BAR; PG8_SCHED;
	s_mov_b32 m0, s56
	v_lshl_add_u64 v[202:203], v[202:203], 0, s[86:87]
	s_add_u32 s24, s24, 0x40080
	ds_read_b128 v[172:175], v135 offset:49152
	ds_read_b128 v[176:179], v135 offset:50176
	ds_read_b128 v[180:183], v135 offset:51200
	ds_read_b128 v[184:187], v135 offset:52224
	ds_read_b128 v[194:197], v135 offset:53248
	ds_read_b128 v[198:201], v135 offset:54272
	ds_read_b128 v[212:215], v135 offset:55296
	ds_read_b128 v[216:219], v135 offset:56320
	global_load_lds_dwordx4 v[202:203], off
	v_lshl_add_u64 v[202:203], v[204:205], 0, s[86:87]
	s_mov_b32 m0, s57
	s_addc_u32 s25, s25, 0
	global_load_lds_dwordx4 v[202:203], off
	v_lshl_add_u64 v[202:203], s[24:25], 0, v[128:129]
	s_mov_b32 m0, s61
	s_nop 0
	global_load_lds_dwordx4 v[202:203], off
	v_lshl_add_u64 v[202:203], s[24:25], 0, v[130:131]
	s_mov_b32 m0, s62
	s_nop 0
	global_load_lds_dwordx4 v[202:203], off
	v_lshl_add_u64 v[202:203], v[220:221], 0, s[86:87]
	s_mov_b32 m0, s58
	s_nop 0
	global_load_lds_dwordx4 v[202:203], off
	v_lshl_add_u64 v[202:203], v[222:223], 0, s[86:87]
	s_mov_b32 m0, s59
	s_nop 0
	global_load_lds_dwordx4 v[202:203], off
	s_waitcnt vmcnt(8)
	s_waitcnt lgkmcnt(0)
	s_barrier
	s_setprio 1
	s_waitcnt lgkmcnt(0)
	v_mfma_f32_16x16x32_bf16 v[60:63], v[136:139], v[172:175], v[60:63]
	v_mfma_f32_16x16x32_bf16 v[56:59], v[148:151], v[172:175], v[56:59]
	v_mfma_f32_16x16x32_bf16 v[44:47], v[136:139], v[180:183], v[44:47]
	v_mfma_f32_16x16x32_bf16 v[40:43], v[148:151], v[180:183], v[40:43]
	v_mfma_f32_16x16x32_bf16 v[28:31], v[136:139], v[194:197], v[28:31]
	v_mfma_f32_16x16x32_bf16 v[24:27], v[148:151], v[194:197], v[24:27]
	v_mfma_f32_16x16x32_bf16 v[12:15], v[136:139], v[212:215], v[12:15]
	v_mfma_f32_16x16x32_bf16 v[8:11], v[148:151], v[212:215], v[8:11]
	v_mfma_f32_16x16x32_bf16 v[60:63], v[144:147], v[176:179], v[60:63]
	v_mfma_f32_16x16x32_bf16 v[56:59], v[152:155], v[176:179], v[56:59]
	v_mfma_f32_16x16x32_bf16 v[44:47], v[144:147], v[184:187], v[44:47]
	v_mfma_f32_16x16x32_bf16 v[40:43], v[152:155], v[184:187], v[40:43]
	v_mfma_f32_16x16x32_bf16 v[28:31], v[144:147], v[198:201], v[28:31]
	v_mfma_f32_16x16x32_bf16 v[24:27], v[152:155], v[198:201], v[24:27]
	v_mfma_f32_16x16x32_bf16 v[12:15], v[144:147], v[216:219], v[12:15]
	v_mfma_f32_16x16x32_bf16 v[8:11], v[152:155], v[216:219], v[8:11]
	v_mfma_f32_16x16x32_bf16 v[52:55], v[156:159], v[172:175], v[52:55]
	v_mfma_f32_16x16x32_bf16 v[48:51], v[164:167], v[172:175], v[48:51]
	v_mfma_f32_16x16x32_bf16 v[36:39], v[156:159], v[180:183], v[36:39]
	v_mfma_f32_16x16x32_bf16 v[32:35], v[164:167], v[180:183], v[32:35]
	v_mfma_f32_16x16x32_bf16 v[20:23], v[156:159], v[194:197], v[20:23]
	v_mfma_f32_16x16x32_bf16 v[16:19], v[164:167], v[194:197], v[16:19]
	v_mfma_f32_16x16x32_bf16 v[4:7], v[156:159], v[212:215], v[4:7]
	v_mfma_f32_16x16x32_bf16 v[0:3], v[164:167], v[212:215], v[0:3]
	v_mfma_f32_16x16x32_bf16 v[52:55], v[160:163], v[176:179], v[52:55]
	v_mfma_f32_16x16x32_bf16 v[48:51], v[168:171], v[176:179], v[48:51]
	v_mfma_f32_16x16x32_bf16 v[36:39], v[160:163], v[184:187], v[36:39]
	v_mfma_f32_16x16x32_bf16 v[32:35], v[168:171], v[184:187], v[32:35]
	v_mfma_f32_16x16x32_bf16 v[20:23], v[160:163], v[198:201], v[20:23]
	v_mfma_f32_16x16x32_bf16 v[16:19], v[168:171], v[198:201], v[16:19]
	v_mfma_f32_16x16x32_bf16 v[4:7], v[160:163], v[216:219], v[4:7]
	v_mfma_f32_16x16x32_bf16 v[0:3], v[168:171], v[216:219], v[0:3]
	s_setprio 0
	s_barrier
	s_add_i32 s29, s29, 2
	s_add_u32 s4, s4, 0x100
	s_addc_u32 s5, s5, 0
	s_add_u32 s17, s17, 0x100
	s_addc_u32 s28, s28, 0

; #define PG8_STAGE(bufoff, gbase, voff) do { _Pragma("unroll") for (int _i = 0; _i < 2; ++_i) \
;         __builtin_amdgcn_global_load_lds((const unsigned*)((const char*)(gbase) + (voff)[_i]), (PG8_LAS unsigned*)(lds + (bufoff) + ldsw + _i * 8192), 16, 0, 0); } while (0)
; #define PG8_LDA(dst, b, h) do { _Pragma("unroll") for (int m = 0; m < 4; ++m) _Pragma("unroll") for (int k = 0; k < 2; ++k) dst[m][k] = *(const PG8_LAS bf16x8*)(lds + PG8_SA(b, h) + aoff + m * 2048 + k * 1024); } while (0)
; #define PG8_LDB(dst, b, h) do { _Pragma("unroll") for (int n = 0; n < 2; ++n) _Pragma("unroll") for (int k = 0; k < 2; ++k) dst[n][k] = *(const PG8_LAS bf16x8*)(lds + PG8_SB(b, h) + boff + n * 2048 + k * 1024); } while (0)
; #define PG8_MMA(ai, bj, At, Bt) do { __builtin_amdgcn_s_setprio(1); _Pragma("unroll") for (int m = 0; m < 4; ++m) _Pragma("unroll") for (int n = 0; n < 2; ++n) _Pragma("unroll") for (int k = 0; k < 2; ++k) \
;         acc[ai][bj][m][n] = __builtin_amdgcn_mfma_f32_16x16x32_bf16(Bt[n][k], At[m][k], acc[ai][bj][m][n], 0, 0, 0); __builtin_amdgcn_s_setprio(0); } while (0)
; #define PG8_WAIT_V(n) asm volatile("s_waitcnt vmcnt(" #n ")" ::: "memory")
; #define PG8_WAIT_L(n) asm volatile("s_waitcnt lgkmcnt(" #n ")" ::: "memory")
; template <class Epi, class Sched, bool ALIGN_EPI = false, bool SP2 = false>
; __device__ __forceinline__ void gemm_phase(PG8_LAS unsigned char* lds, const int Kdim, const Sched& S, const Epi& E) {
;     ...
;         for (int t = 0; t < nt; t += 2) {
;             const bool last = (t == nt - 2);
;             const char* a1 = cA + (size_t)(t + 1) * kstep;
;             const char* a2 = last ? nA : cA + (size_t)(t + 2) * kstep; const char* b2 = last ? nB : cB + (size_t)(t + 2) * kstep;
;             const char* a3 = a2 + kstep; const char* b3 = b2 + kstep;
;             if constexpr (SP2) {
;             PG8_LDB(B0, 0, 0); PG8_LDB(B1, 0, 1); PG8_SCHED; PG8_LDA(At, 0, 0); PG8_STAGE(PG8_SA(1, 1), a1 + hstep, voffA);
;             PG8_WAIT_V(8); PG8_WAIT_L(0); PG8_BAR; PG8_MMA(0, 0, At, B0); PG8_MMA(0, 1, At, B1); PG8_BAR; PG8_SCHED;
;             PG8_LDA(At, 0, 1); PG8_STAGE(PG8_SB(0, 0), b2, voffB); PG8_STAGE(PG8_SB(0, 1), b2 + hstep, voffB); PG8_STAGE(PG8_SA(0, 0), a2, voffA);
;             PG8_WAIT_V(8); PG8_WAIT_L(0); PG8_BAR; PG8_MMA(1, 0, At, B0); PG8_MMA(1, 1, At, B1); PG8_BAR; PG8_SCHED;
.LBB0_754:
	s_and_b64 s[8:9], s[36:37], exec
	s_cselect_b32 s3, s27, s5
	s_cselect_b32 s19, s26, s4
	s_cselect_b32 s31, s29, s7
	s_cselect_b32 s35, s28, s6
	s_add_u32 s4, s4, 0x40080
	s_addc_u32 s5, s5, 0
	v_add_u32_e32 v1, s85, v1
	s_add_u32 s40, s6, 0x100
	v_mov_b32_e32 v101, v189
	v_mov_b32_e32 v97, v189
	v_mov_b32_e32 v99, v189
	s_addc_u32 s41, s7, 0
	s_mov_b32 s42, -2
	v_add_u32_e32 v103, s60, v1
	v_add_u32_e32 v148, s70, v102
	v_add_u32_e32 v164, s73, v102
	ds_read_b128 v[136:139], v148
	ds_read_b128 v[140:143], v148 offset:1024
	ds_read_b128 v[144:147], v148 offset:2048
	ds_read_b128 v[148:151], v148 offset:3072
	ds_read_b128 v[152:155], v164
	ds_read_b128 v[156:159], v164 offset:1024
	ds_read_b128 v[160:163], v164 offset:2048
	ds_read_b128 v[164:167], v164 offset:3072
	s_add_u32 s6, s4, 0xfffc0080
	s_addc_u32 s7, s5, -1
	s_cmp_eq_u32 s42, 12
	s_cselect_b32 s9, s3, s7
	s_cselect_b32 s8, s19, s6
	s_cselect_b32 s7, s31, s41
	s_cselect_b32 s6, s35, s40
	v_lshl_add_u64 v[200:201], s[4:5], 0, v[188:189]
	s_add_i32 m0, s80, 0xc000
	ds_read_b128 v[168:171], v103
	ds_read_b128 v[172:175], v103 offset:1024
	ds_read_b128 v[176:179], v103 offset:2048
	ds_read_b128 v[180:183], v103 offset:3072
	ds_read_b128 v[184:187], v103 offset:4096
	ds_read_b128 v[196:199], v103 offset:5120
	ds_read_b128 v[214:217], v103 offset:6144
	ds_read_b128 v[218:221], v103 offset:7168
	global_load_lds_dwordx4 v[200:201], off
	v_lshl_add_u64 v[200:201], s[4:5], 0, v[100:101]
	s_add_i32 m0, s80, 0xe000
	s_nop 0
	global_load_lds_dwordx4 v[200:201], off
	s_waitcnt vmcnt(8)
	s_waitcnt lgkmcnt(0)
	s_barrier
	s_setprio 1
	s_waitcnt lgkmcnt(0)
	v_mfma_f32_16x16x32_bf16 v[124:127], v[136:139], v[168:171], 0
	v_mfma_f32_16x16x32_bf16 v[120:123], v[144:147], v[168:171], 0
	v_mfma_f32_16x16x32_bf16 v[132:135], v[136:139], v[176:179], 0
	v_mfma_f32_16x16x32_bf16 v[116:119], v[144:147], v[176:179], 0
	v_mfma_f32_16x16x32_bf16 v[104:107], v[136:139], v[184:187], 0
	v_mfma_f32_16x16x32_bf16 v[108:111], v[144:147], v[184:187], 0
	v_mfma_f32_16x16x32_bf16 v[68:71], v[136:139], v[214:217], 0
	v_mfma_f32_16x16x32_bf16 v[32:35], v[144:147], v[214:217], 0
	v_mfma_f32_16x16x32_bf16 v[124:127], v[140:143], v[172:175], v[124:127]
	v_mfma_f32_16x16x32_bf16 v[120:123], v[148:151], v[172:175], v[120:123]
	v_mfma_f32_16x16x32_bf16 v[132:135], v[140:143], v[180:183], v[132:135]
	v_mfma_f32_16x16x32_bf16 v[116:119], v[148:151], v[180:183], v[116:119]
	v_mfma_f32_16x16x32_bf16 v[104:107], v[140:143], v[196:199], v[104:107]
	v_mfma_f32_16x16x32_bf16 v[108:111], v[148:151], v[196:199], v[108:111]
	v_mfma_f32_16x16x32_bf16 v[68:71], v[140:143], v[218:221], v[68:71]
	v_mfma_f32_16x16x32_bf16 v[32:35], v[148:151], v[218:221], v[32:35]
	v_mfma_f32_16x16x32_bf16 v[112:115], v[152:155], v[168:171], 0
	v_mfma_f32_16x16x32_bf16 v[56:59], v[160:163], v[168:171], 0
	v_mfma_f32_16x16x32_bf16 v[52:55], v[152:155], v[176:179], 0
	v_mfma_f32_16x16x32_bf16 v[40:43], v[160:163], v[176:179], 0
	v_mfma_f32_16x16x32_bf16 v[92:95], v[152:155], v[184:187], 0
	v_mfma_f32_16x16x32_bf16 v[44:47], v[160:163], v[184:187], 0
	v_mfma_f32_16x16x32_bf16 v[64:67], v[152:155], v[214:217], 0
	v_mfma_f32_16x16x32_bf16 v[36:39], v[160:163], v[214:217], 0
	v_mfma_f32_16x16x32_bf16 v[112:115], v[156:159], v[172:175], v[112:115]
	v_mfma_f32_16x16x32_bf16 v[56:59], v[164:167], v[172:175], v[56:59]
	v_mfma_f32_16x16x32_bf16 v[52:55], v[156:159], v[180:183], v[52:55]
	v_mfma_f32_16x16x32_bf16 v[40:43], v[164:167], v[180:183], v[40:43]
	v_mfma_f32_16x16x32_bf16 v[92:95], v[156:159], v[196:199], v[92:95]
	v_mfma_f32_16x16x32_bf16 v[44:47], v[164:167], v[196:199], v[44:47]
	v_mfma_f32_16x16x32_bf16 v[64:67], v[156:159], v[218:221], v[64:67]
	v_mfma_f32_16x16x32_bf16 v[36:39], v[164:167], v[218:221], v[36:39]
	s_setprio 0
	s_barrier
	s_mov_b32 m0, s71
	v_lshl_add_u64 v[200:201], s[6:7], 0, v[96:97]
	s_add_u32 s44, s6, 0x40000
	ds_read_b128 v[168:171], v103 offset:16384
	ds_read_b128 v[172:175], v103 offset:17408
	ds_read_b128 v[176:179], v103 offset:18432
	ds_read_b128 v[180:183], v103 offset:19456
	ds_read_b128 v[184:187], v103 offset:20480
	ds_read_b128 v[196:199], v103 offset:21504
	ds_read_b128 v[214:217], v103 offset:22528
	ds_read_b128 v[218:221], v103 offset:23552
	global_load_lds_dwordx4 v[200:201], off
	v_lshl_add_u64 v[204:205], s[6:7], 0, v[98:99]
	s_mov_b32 m0, s72
	s_addc_u32 s45, s7, 0
	global_load_lds_dwordx4 v[204:205], off
	v_lshl_add_u64 v[222:223], s[44:45], 0, v[96:97]
	s_mov_b32 m0, s78
	v_lshl_add_u64 v[224:225], s[8:9], 0, v[100:101]
	global_load_lds_dwordx4 v[222:223], off
	v_lshl_add_u64 v[222:223], s[44:45], 0, v[98:99]
	s_mov_b32 m0, s79
	s_nop 0
	global_load_lds_dwordx4 v[222:223], off
	v_lshl_add_u64 v[222:223], s[8:9], 0, v[188:189]
	s_mov_b32 m0, s80
	s_nop 0
	global_load_lds_dwordx4 v[222:223], off
	s_mov_b32 m0, s81
	s_nop 0
	global_load_lds_dwordx4 v[224:225], off
	s_waitcnt vmcnt(8)
	s_waitcnt lgkmcnt(0)
	s_barrier
; #define PG8_STAGE(bufoff, gbase, voff) do { _Pragma("unroll") for (int _i = 0; _i < 2; ++_i) \
;         __builtin_amdgcn_global_load_lds((const unsigned*)((const char*)(gbase) + (voff)[_i]), (PG8_LAS unsigned*)(lds + (bufoff) + ldsw + _i * 8192), 16, 0, 0); } while (0)
; #define PG8_LDA(dst, b, h) do { _Pragma("unroll") for (int m = 0; m < 4; ++m) _Pragma("unroll") for (int k = 0; k < 2; ++k) dst[m][k] = *(const PG8_LAS bf16x8*)(lds + PG8_SA(b, h) + aoff + m * 2048 + k * 1024); } while (0)
; #define PG8_LDB(dst, b, h) do { _Pragma("unroll") for (int n = 0; n < 2; ++n) _Pragma("unroll") for (int k = 0; k < 2; ++k) dst[n][k] = *(const PG8_LAS bf16x8*)(lds + PG8_SB(b, h) + boff + n * 2048 + k * 1024); } while (0)
; #define PG8_MMA(ai, bj, At, Bt) do { __builtin_amdgcn_s_setprio(1); _Pragma("unroll") for (int m = 0; m < 4; ++m) _Pragma("unroll") for (int n = 0; n < 2; ++n) _Pragma("unroll") for (int k = 0; k < 2; ++k) \
;         acc[ai][bj][m][n] = __builtin_amdgcn_mfma_f32_16x16x32_bf16(Bt[n][k], At[m][k], acc[ai][bj][m][n], 0, 0, 0); __builtin_amdgcn_s_setprio(0); } while (0)
; #define PG8_WAIT_V(n) asm volatile("s_waitcnt vmcnt(" #n ")" ::: "memory")
; #define PG8_WAIT_L(n) asm volatile("s_waitcnt lgkmcnt(" #n ")" ::: "memory")
; #define PG8_BAR __builtin_amdgcn_s_barrier()
; #define PG8_SCHED __builtin_amdgcn_sched_barrier(0)
; template <class Epi, class Sched, bool ALIGN_EPI = false, bool SP2 = false>
; __device__ __forceinline__ void gemm_phase(PG8_LAS unsigned char* lds, const int Kdim, const Sched& S, const Epi& E) {
;     ...
;             PG8_WAIT_V(8); PG8_WAIT_L(0); PG8_BAR; PG8_MMA(1, 0, At, B0); PG8_MMA(1, 1, At, B1); PG8_BAR; PG8_SCHED;
;             PG8_LDB(B0, 1, 0); PG8_LDB(B1, 1, 1); PG8_SCHED; PG8_LDA(At, 1, 0); PG8_STAGE(PG8_SA(0, 1), a2 + hstep, voffA);
;             PG8_WAIT_V(8); PG8_WAIT_L(0); PG8_BAR; PG8_MMA(0, 0, At, B0); PG8_MMA(0, 1, At, B1); PG8_BAR; PG8_SCHED;
	s_setprio 1
	s_waitcnt lgkmcnt(0)
	v_mfma_f32_16x16x32_bf16 v[88:91], v[136:139], v[168:171], 0
	v_mfma_f32_16x16x32_bf16 v[28:31], v[144:147], v[168:171], 0
	v_mfma_f32_16x16x32_bf16 v[84:87], v[136:139], v[176:179], 0
	v_mfma_f32_16x16x32_bf16 v[80:83], v[144:147], v[176:179], 0
	v_mfma_f32_16x16x32_bf16 v[76:79], v[136:139], v[184:187], 0
	v_mfma_f32_16x16x32_bf16 v[128:131], v[144:147], v[184:187], 0
	v_mfma_f32_16x16x32_bf16 v[60:63], v[136:139], v[214:217], 0
	v_mfma_f32_16x16x32_bf16 v[4:7], v[144:147], v[214:217], 0
	v_mfma_f32_16x16x32_bf16 v[88:91], v[140:143], v[172:175], v[88:91]
	v_mfma_f32_16x16x32_bf16 v[28:31], v[148:151], v[172:175], v[28:31]
	v_mfma_f32_16x16x32_bf16 v[84:87], v[140:143], v[180:183], v[84:87]
	v_mfma_f32_16x16x32_bf16 v[80:83], v[148:151], v[180:183], v[80:83]
	v_mfma_f32_16x16x32_bf16 v[76:79], v[140:143], v[196:199], v[76:79]
	v_mfma_f32_16x16x32_bf16 v[128:131], v[148:151], v[196:199], v[128:131]
	v_mfma_f32_16x16x32_bf16 v[60:63], v[140:143], v[218:221], v[60:63]
	v_mfma_f32_16x16x32_bf16 v[4:7], v[148:151], v[218:221], v[4:7]
	v_mfma_f32_16x16x32_bf16 v[24:27], v[152:155], v[168:171], 0
	v_mfma_f32_16x16x32_bf16 v[20:23], v[160:163], v[168:171], 0
	v_mfma_f32_16x16x32_bf16 v[16:19], v[152:155], v[176:179], 0
	v_mfma_f32_16x16x32_bf16 v[12:15], v[160:163], v[176:179], 0
	v_mfma_f32_16x16x32_bf16 v[72:75], v[152:155], v[184:187], 0
	v_mfma_f32_16x16x32_bf16 v[8:11], v[160:163], v[184:187], 0
	v_mfma_f32_16x16x32_bf16 v[48:51], v[152:155], v[214:217], 0
	v_mfma_f32_16x16x32_bf16 v[0:3], v[160:163], v[214:217], 0
	v_mfma_f32_16x16x32_bf16 v[24:27], v[156:159], v[172:175], v[24:27]
	v_mfma_f32_16x16x32_bf16 v[20:23], v[164:167], v[172:175], v[20:23]
	v_mfma_f32_16x16x32_bf16 v[16:19], v[156:159], v[180:183], v[16:19]
	v_mfma_f32_16x16x32_bf16 v[12:15], v[164:167], v[180:183], v[12:15]
	v_mfma_f32_16x16x32_bf16 v[72:75], v[156:159], v[196:199], v[72:75]
	v_mfma_f32_16x16x32_bf16 v[8:11], v[164:167], v[196:199], v[8:11]
	v_mfma_f32_16x16x32_bf16 v[48:51], v[156:159], v[218:221], v[48:51]
	v_mfma_f32_16x16x32_bf16 v[0:3], v[164:167], v[218:221], v[0:3]
	s_setprio 0
	s_barrier
	v_add_u32_e32 v148, s90, v102
	v_add_u32_e32 v164, s97, v102
	ds_read_b128 v[136:139], v148
	ds_read_b128 v[140:143], v148 offset:1024
	ds_read_b128 v[144:147], v148 offset:2048
	ds_read_b128 v[148:151], v148 offset:3072
	ds_read_b128 v[152:155], v164
	ds_read_b128 v[156:159], v164 offset:1024
	ds_read_b128 v[160:163], v164 offset:2048
	ds_read_b128 v[164:167], v164 offset:3072
	s_add_u32 s8, s8, 0x40000
	s_addc_u32 s9, s9, 0
	s_mov_b32 m0, s82
	v_lshl_add_u64 v[226:227], s[8:9], 0, v[188:189]
	ds_read_b128 v[168:171], v103 offset:32768
	ds_read_b128 v[172:175], v103 offset:33792
	ds_read_b128 v[176:179], v103 offset:34816
	ds_read_b128 v[180:183], v103 offset:35840
	ds_read_b128 v[184:187], v103 offset:36864
	ds_read_b128 v[196:199], v103 offset:37888
	ds_read_b128 v[214:217], v103 offset:38912
	ds_read_b128 v[218:221], v103 offset:39936
	global_load_lds_dwordx4 v[226:227], off
	v_lshl_add_u64 v[226:227], s[8:9], 0, v[100:101]
	s_mov_b32 m0, s83
	s_nop 0
	global_load_lds_dwordx4 v[226:227], off
	s_waitcnt vmcnt(8)
	s_waitcnt lgkmcnt(0)
	s_barrier
	s_setprio 1
	s_waitcnt lgkmcnt(0)
	v_mfma_f32_16x16x32_bf16 v[124:127], v[136:139], v[168:171], v[124:127]
	v_mfma_f32_16x16x32_bf16 v[120:123], v[144:147], v[168:171], v[120:123]
	v_mfma_f32_16x16x32_bf16 v[132:135], v[136:139], v[176:179], v[132:135]
	v_mfma_f32_16x16x32_bf16 v[116:119], v[144:147], v[176:179], v[116:119]
	v_mfma_f32_16x16x32_bf16 v[104:107], v[136:139], v[184:187], v[104:107]
	v_mfma_f32_16x16x32_bf16 v[108:111], v[144:147], v[184:187], v[108:111]
	v_mfma_f32_16x16x32_bf16 v[68:71], v[136:139], v[214:217], v[68:71]
	v_mfma_f32_16x16x32_bf16 v[32:35], v[144:147], v[214:217], v[32:35]
	v_mfma_f32_16x16x32_bf16 v[124:127], v[140:143], v[172:175], v[124:127]
	v_mfma_f32_16x16x32_bf16 v[120:123], v[148:151], v[172:175], v[120:123]
	v_mfma_f32_16x16x32_bf16 v[132:135], v[140:143], v[180:183], v[132:135]
	v_mfma_f32_16x16x32_bf16 v[116:119], v[148:151], v[180:183], v[116:119]
	v_mfma_f32_16x16x32_bf16 v[104:107], v[140:143], v[196:199], v[104:107]
	v_mfma_f32_16x16x32_bf16 v[108:111], v[148:151], v[196:199], v[108:111]
	v_mfma_f32_16x16x32_bf16 v[68:71], v[140:143], v[218:221], v[68:71]
	v_mfma_f32_16x16x32_bf16 v[32:35], v[148:151], v[218:221], v[32:35]
	v_mfma_f32_16x16x32_bf16 v[112:115], v[152:155], v[168:171], v[112:115]
	v_mfma_f32_16x16x32_bf16 v[56:59], v[160:163], v[168:171], v[56:59]
	v_mfma_f32_16x16x32_bf16 v[52:55], v[152:155], v[176:179], v[52:55]
	v_mfma_f32_16x16x32_bf16 v[40:43], v[160:163], v[176:179], v[40:43]
	v_mfma_f32_16x16x32_bf16 v[92:95], v[152:155], v[184:187], v[92:95]
	v_mfma_f32_16x16x32_bf16 v[44:47], v[160:163], v[184:187], v[44:47]
	v_mfma_f32_16x16x32_bf16 v[64:67], v[152:155], v[214:217], v[64:67]
	v_mfma_f32_16x16x32_bf16 v[36:39], v[160:163], v[214:217], v[36:39]
	v_mfma_f32_16x16x32_bf16 v[112:115], v[156:159], v[172:175], v[112:115]
	v_mfma_f32_16x16x32_bf16 v[56:59], v[164:167], v[172:175], v[56:59]
	v_mfma_f32_16x16x32_bf16 v[52:55], v[156:159], v[180:183], v[52:55]
	v_mfma_f32_16x16x32_bf16 v[40:43], v[164:167], v[180:183], v[40:43]
	v_mfma_f32_16x16x32_bf16 v[92:95], v[156:159], v[196:199], v[92:95]
	v_mfma_f32_16x16x32_bf16 v[44:47], v[164:167], v[196:199], v[44:47]
	v_mfma_f32_16x16x32_bf16 v[64:67], v[156:159], v[218:221], v[64:67]
	v_mfma_f32_16x16x32_bf16 v[36:39], v[164:167], v[218:221], v[36:39]
	s_setprio 0
	s_barrier
; #define PG8_STAGE(bufoff, gbase, voff) do { _Pragma("unroll") for (int _i = 0; _i < 2; ++_i) \
;         __builtin_amdgcn_global_load_lds((const unsigned*)((const char*)(gbase) + (voff)[_i]), (PG8_LAS unsigned*)(lds + (bufoff) + ldsw + _i * 8192), 16, 0, 0); } while (0)
; #define PG8_LDA(dst, b, h) do { _Pragma("unroll") for (int m = 0; m < 4; ++m) _Pragma("unroll") for (int k = 0; k < 2; ++k) dst[m][k] = *(const PG8_LAS bf16x8*)(lds + PG8_SA(b, h) + aoff + m * 2048 + k * 1024); } while (0)
; #define PG8_MMA(ai, bj, At, Bt) do { __builtin_amdgcn_s_setprio(1); _Pragma("unroll") for (int m = 0; m < 4; ++m) _Pragma("unroll") for (int n = 0; n < 2; ++n) _Pragma("unroll") for (int k = 0; k < 2; ++k) \
;         acc[ai][bj][m][n] = __builtin_amdgcn_mfma_f32_16x16x32_bf16(Bt[n][k], At[m][k], acc[ai][bj][m][n], 0, 0, 0); __builtin_amdgcn_s_setprio(0); } while (0)
; #define PG8_WAIT_V(n) asm volatile("s_waitcnt vmcnt(" #n ")" ::: "memory")
; #define PG8_WAIT_L(n) asm volatile("s_waitcnt lgkmcnt(" #n ")" ::: "memory")
; #define PG8_BAR __builtin_amdgcn_s_barrier()
; #define PG8_SCHED __builtin_amdgcn_sched_barrier(0)
; template <class Epi, class Sched, bool ALIGN_EPI = false, bool SP2 = false>
; __device__ __forceinline__ void gemm_phase(PG8_LAS unsigned char* lds, const int Kdim, const Sched& S, const Epi& E) {
;     ...
;             PG8_LDA(At, 1, 1); PG8_STAGE(PG8_SB(1, 0), b3, voffB); PG8_STAGE(PG8_SB(1, 1), b3 + hstep, voffB); PG8_STAGE(PG8_SA(1, 0), a3, voffA);
;             PG8_WAIT_V(8); PG8_WAIT_L(0); PG8_BAR; PG8_MMA(1, 0, At, B0); PG8_MMA(1, 1, At, B1); PG8_BAR; PG8_SCHED;
	s_mov_b32 m0, s91
	v_lshl_add_u64 v[200:201], v[200:201], 0, s[86:87]
	s_add_u32 s6, s6, 0x40080
	ds_read_b128 v[168:171], v103 offset:49152
	ds_read_b128 v[172:175], v103 offset:50176
	ds_read_b128 v[176:179], v103 offset:51200
	ds_read_b128 v[180:183], v103 offset:52224
	ds_read_b128 v[184:187], v103 offset:53248
	ds_read_b128 v[196:199], v103 offset:54272
	ds_read_b128 v[214:217], v103 offset:55296
	ds_read_b128 v[218:221], v103 offset:56320
	global_load_lds_dwordx4 v[200:201], off
	v_lshl_add_u64 v[200:201], v[204:205], 0, s[86:87]
	s_mov_b32 m0, s94
	s_addc_u32 s7, s7, 0
	global_load_lds_dwordx4 v[200:201], off
	v_lshl_add_u64 v[200:201], s[6:7], 0, v[96:97]
	s_mov_b32 m0, s77
	s_nop 0
	global_load_lds_dwordx4 v[200:201], off
	v_lshl_add_u64 v[200:201], s[6:7], 0, v[98:99]
	s_mov_b32 m0, s10
	s_nop 0
	global_load_lds_dwordx4 v[200:201], off
	v_lshl_add_u64 v[200:201], v[222:223], 0, s[86:87]
	s_mov_b32 m0, s95
	s_nop 0
	global_load_lds_dwordx4 v[200:201], off
	v_lshl_add_u64 v[200:201], v[224:225], 0, s[86:87]
	s_mov_b32 m0, s96
	s_nop 0
	global_load_lds_dwordx4 v[200:201], off
	s_waitcnt vmcnt(8)
	s_waitcnt lgkmcnt(0)
	s_barrier
	s_setprio 1
	s_waitcnt lgkmcnt(0)
	v_mfma_f32_16x16x32_bf16 v[88:91], v[136:139], v[168:171], v[88:91]
	v_mfma_f32_16x16x32_bf16 v[28:31], v[144:147], v[168:171], v[28:31]
	v_mfma_f32_16x16x32_bf16 v[84:87], v[136:139], v[176:179], v[84:87]
	v_mfma_f32_16x16x32_bf16 v[80:83], v[144:147], v[176:179], v[80:83]
	v_mfma_f32_16x16x32_bf16 v[76:79], v[136:139], v[184:187], v[76:79]
	v_mfma_f32_16x16x32_bf16 v[128:131], v[144:147], v[184:187], v[128:131]
	v_mfma_f32_16x16x32_bf16 v[60:63], v[136:139], v[214:217], v[60:63]
	v_mfma_f32_16x16x32_bf16 v[4:7], v[144:147], v[214:217], v[4:7]
	v_mfma_f32_16x16x32_bf16 v[88:91], v[140:143], v[172:175], v[88:91]
	v_mfma_f32_16x16x32_bf16 v[28:31], v[148:151], v[172:175], v[28:31]
	v_mfma_f32_16x16x32_bf16 v[84:87], v[140:143], v[180:183], v[84:87]
	v_mfma_f32_16x16x32_bf16 v[80:83], v[148:151], v[180:183], v[80:83]
	v_mfma_f32_16x16x32_bf16 v[76:79], v[140:143], v[196:199], v[76:79]
	v_mfma_f32_16x16x32_bf16 v[128:131], v[148:151], v[196:199], v[128:131]
	v_mfma_f32_16x16x32_bf16 v[60:63], v[140:143], v[218:221], v[60:63]
	v_mfma_f32_16x16x32_bf16 v[4:7], v[148:151], v[218:221], v[4:7]
	v_mfma_f32_16x16x32_bf16 v[24:27], v[152:155], v[168:171], v[24:27]
	v_mfma_f32_16x16x32_bf16 v[20:23], v[160:163], v[168:171], v[20:23]
	v_mfma_f32_16x16x32_bf16 v[16:19], v[152:155], v[176:179], v[16:19]
	v_mfma_f32_16x16x32_bf16 v[12:15], v[160:163], v[176:179], v[12:15]
	v_mfma_f32_16x16x32_bf16 v[72:75], v[152:155], v[184:187], v[72:75]
	v_mfma_f32_16x16x32_bf16 v[8:11], v[160:163], v[184:187], v[8:11]
	v_mfma_f32_16x16x32_bf16 v[48:51], v[152:155], v[214:217], v[48:51]
	v_mfma_f32_16x16x32_bf16 v[0:3], v[160:163], v[214:217], v[0:3]
	v_mfma_f32_16x16x32_bf16 v[24:27], v[156:159], v[172:175], v[24:27]
	v_mfma_f32_16x16x32_bf16 v[20:23], v[164:167], v[172:175], v[20:23]
	v_mfma_f32_16x16x32_bf16 v[16:19], v[156:159], v[180:183], v[16:19]
	v_mfma_f32_16x16x32_bf16 v[12:15], v[164:167], v[180:183], v[12:15]
	v_mfma_f32_16x16x32_bf16 v[72:75], v[156:159], v[196:199], v[72:75]
	v_mfma_f32_16x16x32_bf16 v[8:11], v[164:167], v[196:199], v[8:11]
	v_mfma_f32_16x16x32_bf16 v[48:51], v[156:159], v[218:221], v[48:51]
	v_mfma_f32_16x16x32_bf16 v[0:3], v[164:167], v[218:221], v[0:3]
	s_setprio 0
	s_barrier
	s_add_i32 s42, s42, 2
	s_add_u32 s4, s4, 0x100
	s_addc_u32 s5, s5, 0
	s_add_u32 s40, s40, 0x100
	s_addc_u32 s41, s41, 0

; #define PG8_STAGE(bufoff, gbase, voff) do { _Pragma("unroll") for (int _i = 0; _i < 2; ++_i) \
;         __builtin_amdgcn_global_load_lds((const unsigned*)((const char*)(gbase) + (voff)[_i]), (PG8_LAS unsigned*)(lds + (bufoff) + ldsw + _i * 8192), 16, 0, 0); } while (0)
; #define PG8_LDA(dst, b, h) do { _Pragma("unroll") for (int m = 0; m < 4; ++m) _Pragma("unroll") for (int k = 0; k < 2; ++k) dst[m][k] = *(const PG8_LAS bf16x8*)(lds + PG8_SA(b, h) + aoff + m * 2048 + k * 1024); } while (0)
; #define PG8_LDB(dst, b, h) do { _Pragma("unroll") for (int n = 0; n < 2; ++n) _Pragma("unroll") for (int k = 0; k < 2; ++k) dst[n][k] = *(const PG8_LAS bf16x8*)(lds + PG8_SB(b, h) + boff + n * 2048 + k * 1024); } while (0)
; #define PG8_MMA(ai, bj, At, Bt) do { __builtin_amdgcn_s_setprio(1); _Pragma("unroll") for (int m = 0; m < 4; ++m) _Pragma("unroll") for (int n = 0; n < 2; ++n) _Pragma("unroll") for (int k = 0; k < 2; ++k) \
;         acc[ai][bj][m][n] = __builtin_amdgcn_mfma_f32_16x16x32_bf16(Bt[n][k], At[m][k], acc[ai][bj][m][n], 0, 0, 0); __builtin_amdgcn_s_setprio(0); } while (0)
; #define PG8_WAIT_V(n) asm volatile("s_waitcnt vmcnt(" #n ")" ::: "memory")
; #define PG8_WAIT_L(n) asm volatile("s_waitcnt lgkmcnt(" #n ")" ::: "memory")
; template <class Epi, class Sched, bool ALIGN_EPI = false, bool SP2 = false>
; __device__ __forceinline__ void gemm_phase(PG8_LAS unsigned char* lds, const int Kdim, const Sched& S, const Epi& E) {
;     ...
;         for (int t = 0; t < nt; t += 2) {
;             const bool last = (t == nt - 2);
;             const char* a1 = cA + (size_t)(t + 1) * kstep;
;             const char* a2 = last ? nA : cA + (size_t)(t + 2) * kstep; const char* b2 = last ? nB : cB + (size_t)(t + 2) * kstep;
;             const char* a3 = a2 + kstep; const char* b3 = b2 + kstep;
;             if constexpr (SP2) {
;             PG8_LDB(B0, 0, 0); PG8_LDB(B1, 0, 1); PG8_SCHED; PG8_LDA(At, 0, 0); PG8_STAGE(PG8_SA(1, 1), a1 + hstep, voffA);
;             PG8_WAIT_V(8); PG8_WAIT_L(0); PG8_BAR; PG8_MMA(0, 0, At, B0); PG8_MMA(0, 1, At, B1); PG8_BAR; PG8_SCHED;
;             PG8_LDA(At, 0, 1); PG8_STAGE(PG8_SB(0, 0), b2, voffB); PG8_STAGE(PG8_SB(0, 1), b2 + hstep, voffB); PG8_STAGE(PG8_SA(0, 0), a2, voffA);
;             PG8_WAIT_V(8); PG8_WAIT_L(0); PG8_BAR; PG8_MMA(1, 0, At, B0); PG8_MMA(1, 1, At, B1); PG8_BAR; PG8_SCHED;
.LBB0_978:
	s_and_b64 s[30:31], s[22:23], exec
	s_cselect_b32 s7, s19, s27
	s_cselect_b32 s25, s18, s26
	s_cselect_b32 s34, s21, s29
	s_cselect_b32 s35, s20, s28
	s_add_i32 s80, s1, -2
	s_add_u32 s26, s26, 0xb0080
	s_addc_u32 s27, s27, 0
	v_add_u32_e32 v2, s56, v0
	s_add_u32 s81, s28, 0x100
	s_waitcnt lgkmcnt(0)
	v_add_u32_e32 v134, s58, v1
	v_mov_b32_e32 v131, v189
	v_mov_b32_e32 v129, v189
	v_mov_b32_e32 v133, v189
	s_addc_u32 s82, s29, 0
	s_mov_b32 s28, 0
	v_add_u32_e32 v135, s36, v2
	v_add_u32_e32 v142, s45, v134
	ds_read_b128 v[138:141], v142
	ds_read_b128 v[148:151], v142 offset:1024
	ds_read_b128 v[152:155], v142 offset:2048
	ds_read_b128 v[156:159], v142 offset:3072
	v_add_u32_e32 v142, s48, v134
	ds_read_b128 v[160:163], v142
	ds_read_b128 v[164:167], v142 offset:1024
	ds_read_b128 v[168:171], v142 offset:2048
	ds_read_b128 v[172:175], v142 offset:3072
	s_add_i32 s83, s28, 2
	s_add_u32 s29, s26, 0xfff50080
	s_addc_u32 s30, s27, -1
	s_cmp_eq_u32 s80, s28
	s_cselect_b32 s28, s35, s81
	s_cselect_b32 s31, s7, s30
	s_cselect_b32 s30, s25, s29
	s_cselect_b32 s29, s34, s82
	v_lshl_add_u64 v[142:143], s[26:27], 0, v[188:189]
	s_add_i32 m0, s51, 0xc000
	ds_read_b128 v[176:179], v135
	ds_read_b128 v[180:183], v135 offset:1024
	ds_read_b128 v[184:187], v135 offset:2048
	ds_read_b128 v[194:197], v135 offset:3072
	ds_read_b128 v[198:201], v135 offset:4096
	ds_read_b128 v[212:215], v135 offset:5120
	ds_read_b128 v[216:219], v135 offset:6144
	ds_read_b128 v[220:223], v135 offset:7168
	global_load_lds_dwordx4 v[142:143], off
	v_lshl_add_u64 v[142:143], s[26:27], 0, v[130:131]
	s_add_i32 m0, s51, 0xe000
	s_nop 0
	global_load_lds_dwordx4 v[142:143], off
	s_waitcnt vmcnt(8)
	s_waitcnt lgkmcnt(0)
	s_barrier
	s_setprio 1
	s_waitcnt lgkmcnt(0)
	v_mfma_f32_16x16x32_bf16 v[124:127], v[138:141], v[176:179], 0
	v_mfma_f32_16x16x32_bf16 v[120:123], v[152:155], v[176:179], 0
	v_mfma_f32_16x16x32_bf16 v[108:111], v[138:141], v[184:187], 0
	v_mfma_f32_16x16x32_bf16 v[104:107], v[152:155], v[184:187], 0
	v_mfma_f32_16x16x32_bf16 v[92:95], v[138:141], v[198:201], 0
	v_mfma_f32_16x16x32_bf16 v[88:91], v[152:155], v[198:201], 0
	v_mfma_f32_16x16x32_bf16 v[76:79], v[138:141], v[216:219], 0
	v_mfma_f32_16x16x32_bf16 v[72:75], v[152:155], v[216:219], 0
	v_mfma_f32_16x16x32_bf16 v[124:127], v[148:151], v[180:183], v[124:127]
	v_mfma_f32_16x16x32_bf16 v[120:123], v[156:159], v[180:183], v[120:123]
	v_mfma_f32_16x16x32_bf16 v[108:111], v[148:151], v[194:197], v[108:111]
	v_mfma_f32_16x16x32_bf16 v[104:107], v[156:159], v[194:197], v[104:107]
	v_mfma_f32_16x16x32_bf16 v[92:95], v[148:151], v[212:215], v[92:95]
	v_mfma_f32_16x16x32_bf16 v[88:91], v[156:159], v[212:215], v[88:91]
	v_mfma_f32_16x16x32_bf16 v[76:79], v[148:151], v[220:223], v[76:79]
	v_mfma_f32_16x16x32_bf16 v[72:75], v[156:159], v[220:223], v[72:75]
	v_mfma_f32_16x16x32_bf16 v[116:119], v[160:163], v[176:179], 0
	v_mfma_f32_16x16x32_bf16 v[112:115], v[168:171], v[176:179], 0
	v_mfma_f32_16x16x32_bf16 v[100:103], v[160:163], v[184:187], 0
	v_mfma_f32_16x16x32_bf16 v[96:99], v[168:171], v[184:187], 0
	v_mfma_f32_16x16x32_bf16 v[84:87], v[160:163], v[198:201], 0
	v_mfma_f32_16x16x32_bf16 v[80:83], v[168:171], v[198:201], 0
	v_mfma_f32_16x16x32_bf16 v[68:71], v[160:163], v[216:219], 0
	v_mfma_f32_16x16x32_bf16 v[64:67], v[168:171], v[216:219], 0
	v_mfma_f32_16x16x32_bf16 v[116:119], v[164:167], v[180:183], v[116:119]
	v_mfma_f32_16x16x32_bf16 v[112:115], v[172:175], v[180:183], v[112:115]
	v_mfma_f32_16x16x32_bf16 v[100:103], v[164:167], v[194:197], v[100:103]
	v_mfma_f32_16x16x32_bf16 v[96:99], v[172:175], v[194:197], v[96:99]
	v_mfma_f32_16x16x32_bf16 v[84:87], v[164:167], v[212:215], v[84:87]
	v_mfma_f32_16x16x32_bf16 v[80:83], v[172:175], v[212:215], v[80:83]
	v_mfma_f32_16x16x32_bf16 v[68:71], v[164:167], v[220:223], v[68:71]
	v_mfma_f32_16x16x32_bf16 v[64:67], v[172:175], v[220:223], v[64:67]
	s_setprio 0
	s_barrier
	s_mov_b32 m0, s46
	v_lshl_add_u64 v[142:143], s[28:29], 0, v[128:129]
	s_add_u32 s84, s28, 0xb0000
	ds_read_b128 v[176:179], v135 offset:16384
	ds_read_b128 v[180:183], v135 offset:17408
	ds_read_b128 v[184:187], v135 offset:18432
	ds_read_b128 v[194:197], v135 offset:19456
	ds_read_b128 v[198:201], v135 offset:20480
	ds_read_b128 v[212:215], v135 offset:21504
	ds_read_b128 v[216:219], v135 offset:22528
	ds_read_b128 v[220:223], v135 offset:23552
	global_load_lds_dwordx4 v[142:143], off
	v_lshl_add_u64 v[202:203], s[28:29], 0, v[132:133]
	s_mov_b32 m0, s47
	s_addc_u32 s85, s29, 0
	global_load_lds_dwordx4 v[202:203], off
	v_lshl_add_u64 v[204:205], s[84:85], 0, v[128:129]
	s_mov_b32 m0, s49
	v_lshl_add_u64 v[224:225], s[30:31], 0, v[130:131]
	global_load_lds_dwordx4 v[204:205], off
	v_lshl_add_u64 v[204:205], s[84:85], 0, v[132:133]
	s_mov_b32 m0, s50
	s_nop 0
	global_load_lds_dwordx4 v[204:205], off
	v_lshl_add_u64 v[204:205], s[30:31], 0, v[188:189]
	s_mov_b32 m0, s51
	s_nop 0
	global_load_lds_dwordx4 v[204:205], off
	s_mov_b32 m0, s52
	s_nop 0
	global_load_lds_dwordx4 v[224:225], off
	s_waitcnt vmcnt(8)
	s_waitcnt lgkmcnt(0)
	s_barrier
; #define PG8_STAGE(bufoff, gbase, voff) do { _Pragma("unroll") for (int _i = 0; _i < 2; ++_i) \
;         __builtin_amdgcn_global_load_lds((const unsigned*)((const char*)(gbase) + (voff)[_i]), (PG8_LAS unsigned*)(lds + (bufoff) + ldsw + _i * 8192), 16, 0, 0); } while (0)
; #define PG8_LDA(dst, b, h) do { _Pragma("unroll") for (int m = 0; m < 4; ++m) _Pragma("unroll") for (int k = 0; k < 2; ++k) dst[m][k] = *(const PG8_LAS bf16x8*)(lds + PG8_SA(b, h) + aoff + m * 2048 + k * 1024); } while (0)
; #define PG8_LDB(dst, b, h) do { _Pragma("unroll") for (int n = 0; n < 2; ++n) _Pragma("unroll") for (int k = 0; k < 2; ++k) dst[n][k] = *(const PG8_LAS bf16x8*)(lds + PG8_SB(b, h) + boff + n * 2048 + k * 1024); } while (0)
; #define PG8_MMA(ai, bj, At, Bt) do { __builtin_amdgcn_s_setprio(1); _Pragma("unroll") for (int m = 0; m < 4; ++m) _Pragma("unroll") for (int n = 0; n < 2; ++n) _Pragma("unroll") for (int k = 0; k < 2; ++k) \
;         acc[ai][bj][m][n] = __builtin_amdgcn_mfma_f32_16x16x32_bf16(Bt[n][k], At[m][k], acc[ai][bj][m][n], 0, 0, 0); __builtin_amdgcn_s_setprio(0); } while (0)
; #define PG8_WAIT_V(n) asm volatile("s_waitcnt vmcnt(" #n ")" ::: "memory")
; #define PG8_WAIT_L(n) asm volatile("s_waitcnt lgkmcnt(" #n ")" ::: "memory")
; #define PG8_BAR __builtin_amdgcn_s_barrier()
; #define PG8_SCHED __builtin_amdgcn_sched_barrier(0)
; template <class Epi, class Sched, bool ALIGN_EPI = false, bool SP2 = false>
; __device__ __forceinline__ void gemm_phase(PG8_LAS unsigned char* lds, const int Kdim, const Sched& S, const Epi& E) {
;     ...
;             PG8_WAIT_V(8); PG8_WAIT_L(0); PG8_BAR; PG8_MMA(1, 0, At, B0); PG8_MMA(1, 1, At, B1); PG8_BAR; PG8_SCHED;
;             PG8_LDB(B0, 1, 0); PG8_LDB(B1, 1, 1); PG8_SCHED; PG8_LDA(At, 1, 0); PG8_STAGE(PG8_SA(0, 1), a2 + hstep, voffA);
;             PG8_WAIT_V(8); PG8_WAIT_L(0); PG8_BAR; PG8_MMA(0, 0, At, B0); PG8_MMA(0, 1, At, B1); PG8_BAR; PG8_SCHED;
	s_setprio 1
	s_waitcnt lgkmcnt(0)
	v_mfma_f32_16x16x32_bf16 v[60:63], v[138:141], v[176:179], 0
	v_mfma_f32_16x16x32_bf16 v[56:59], v[152:155], v[176:179], 0
	v_mfma_f32_16x16x32_bf16 v[44:47], v[138:141], v[184:187], 0
	v_mfma_f32_16x16x32_bf16 v[40:43], v[152:155], v[184:187], 0
	v_mfma_f32_16x16x32_bf16 v[28:31], v[138:141], v[198:201], 0
	v_mfma_f32_16x16x32_bf16 v[24:27], v[152:155], v[198:201], 0
	v_mfma_f32_16x16x32_bf16 v[12:15], v[138:141], v[216:219], 0
	v_mfma_f32_16x16x32_bf16 v[8:11], v[152:155], v[216:219], 0
	v_mfma_f32_16x16x32_bf16 v[60:63], v[148:151], v[180:183], v[60:63]
	v_mfma_f32_16x16x32_bf16 v[56:59], v[156:159], v[180:183], v[56:59]
	v_mfma_f32_16x16x32_bf16 v[44:47], v[148:151], v[194:197], v[44:47]
	v_mfma_f32_16x16x32_bf16 v[40:43], v[156:159], v[194:197], v[40:43]
	v_mfma_f32_16x16x32_bf16 v[28:31], v[148:151], v[212:215], v[28:31]
	v_mfma_f32_16x16x32_bf16 v[24:27], v[156:159], v[212:215], v[24:27]
	v_mfma_f32_16x16x32_bf16 v[12:15], v[148:151], v[220:223], v[12:15]
	v_mfma_f32_16x16x32_bf16 v[8:11], v[156:159], v[220:223], v[8:11]
	v_mfma_f32_16x16x32_bf16 v[52:55], v[160:163], v[176:179], 0
	v_mfma_f32_16x16x32_bf16 v[48:51], v[168:171], v[176:179], 0
	v_mfma_f32_16x16x32_bf16 v[36:39], v[160:163], v[184:187], 0
	v_mfma_f32_16x16x32_bf16 v[32:35], v[168:171], v[184:187], 0
	v_mfma_f32_16x16x32_bf16 v[20:23], v[160:163], v[198:201], 0
	v_mfma_f32_16x16x32_bf16 v[16:19], v[168:171], v[198:201], 0
	v_mfma_f32_16x16x32_bf16 v[4:7], v[160:163], v[216:219], 0
	v_mfma_f32_16x16x32_bf16 v[0:3], v[168:171], v[216:219], 0
	v_mfma_f32_16x16x32_bf16 v[52:55], v[164:167], v[180:183], v[52:55]
	v_mfma_f32_16x16x32_bf16 v[48:51], v[172:175], v[180:183], v[48:51]
	v_mfma_f32_16x16x32_bf16 v[36:39], v[164:167], v[194:197], v[36:39]
	v_mfma_f32_16x16x32_bf16 v[32:35], v[172:175], v[194:197], v[32:35]
	v_mfma_f32_16x16x32_bf16 v[20:23], v[164:167], v[212:215], v[20:23]
	v_mfma_f32_16x16x32_bf16 v[16:19], v[172:175], v[212:215], v[16:19]
	v_mfma_f32_16x16x32_bf16 v[4:7], v[164:167], v[220:223], v[4:7]
	v_mfma_f32_16x16x32_bf16 v[0:3], v[172:175], v[220:223], v[0:3]
	s_setprio 0
	s_barrier
	v_add_u32_e32 v156, s59, v134
	v_add_u32_e32 v172, s64, v134
	ds_read_b128 v[138:141], v156
	ds_read_b128 v[148:151], v156 offset:1024
	ds_read_b128 v[152:155], v156 offset:2048
	ds_read_b128 v[156:159], v156 offset:3072
	ds_read_b128 v[160:163], v172
	ds_read_b128 v[164:167], v172 offset:1024
	ds_read_b128 v[168:171], v172 offset:2048
	ds_read_b128 v[172:175], v172 offset:3072
	s_add_u32 s30, s30, 0xb0000
	s_addc_u32 s31, s31, 0
	s_mov_b32 m0, s53
	v_lshl_add_u64 v[226:227], s[30:31], 0, v[188:189]
	ds_read_b128 v[176:179], v135 offset:32768
	ds_read_b128 v[180:183], v135 offset:33792
	ds_read_b128 v[184:187], v135 offset:34816
	ds_read_b128 v[194:197], v135 offset:35840
	ds_read_b128 v[198:201], v135 offset:36864
	ds_read_b128 v[212:215], v135 offset:37888
	ds_read_b128 v[216:219], v135 offset:38912
	ds_read_b128 v[220:223], v135 offset:39936
	global_load_lds_dwordx4 v[226:227], off
	v_lshl_add_u64 v[226:227], s[30:31], 0, v[130:131]
	s_mov_b32 m0, s54
	s_nop 0
	global_load_lds_dwordx4 v[226:227], off
	s_waitcnt vmcnt(8)
	s_waitcnt lgkmcnt(0)
	s_barrier
	s_setprio 1
	s_waitcnt lgkmcnt(0)
	v_mfma_f32_16x16x32_bf16 v[124:127], v[138:141], v[176:179], v[124:127]
	v_mfma_f32_16x16x32_bf16 v[120:123], v[152:155], v[176:179], v[120:123]
	v_mfma_f32_16x16x32_bf16 v[108:111], v[138:141], v[184:187], v[108:111]
	v_mfma_f32_16x16x32_bf16 v[104:107], v[152:155], v[184:187], v[104:107]
	v_mfma_f32_16x16x32_bf16 v[92:95], v[138:141], v[198:201], v[92:95]
	v_mfma_f32_16x16x32_bf16 v[88:91], v[152:155], v[198:201], v[88:91]
	v_mfma_f32_16x16x32_bf16 v[76:79], v[138:141], v[216:219], v[76:79]
	v_mfma_f32_16x16x32_bf16 v[72:75], v[152:155], v[216:219], v[72:75]
	v_mfma_f32_16x16x32_bf16 v[124:127], v[148:151], v[180:183], v[124:127]
	v_mfma_f32_16x16x32_bf16 v[120:123], v[156:159], v[180:183], v[120:123]
	v_mfma_f32_16x16x32_bf16 v[108:111], v[148:151], v[194:197], v[108:111]
	v_mfma_f32_16x16x32_bf16 v[104:107], v[156:159], v[194:197], v[104:107]
	v_mfma_f32_16x16x32_bf16 v[92:95], v[148:151], v[212:215], v[92:95]
	v_mfma_f32_16x16x32_bf16 v[88:91], v[156:159], v[212:215], v[88:91]
	v_mfma_f32_16x16x32_bf16 v[76:79], v[148:151], v[220:223], v[76:79]
	v_mfma_f32_16x16x32_bf16 v[72:75], v[156:159], v[220:223], v[72:75]
	v_mfma_f32_16x16x32_bf16 v[116:119], v[160:163], v[176:179], v[116:119]
	v_mfma_f32_16x16x32_bf16 v[112:115], v[168:171], v[176:179], v[112:115]
	v_mfma_f32_16x16x32_bf16 v[100:103], v[160:163], v[184:187], v[100:103]
	v_mfma_f32_16x16x32_bf16 v[96:99], v[168:171], v[184:187], v[96:99]
	v_mfma_f32_16x16x32_bf16 v[84:87], v[160:163], v[198:201], v[84:87]
	v_mfma_f32_16x16x32_bf16 v[80:83], v[168:171], v[198:201], v[80:83]
	v_mfma_f32_16x16x32_bf16 v[68:71], v[160:163], v[216:219], v[68:71]
	v_mfma_f32_16x16x32_bf16 v[64:67], v[168:171], v[216:219], v[64:67]
	v_mfma_f32_16x16x32_bf16 v[116:119], v[164:167], v[180:183], v[116:119]
	v_mfma_f32_16x16x32_bf16 v[112:115], v[172:175], v[180:183], v[112:115]
	v_mfma_f32_16x16x32_bf16 v[100:103], v[164:167], v[194:197], v[100:103]
	v_mfma_f32_16x16x32_bf16 v[96:99], v[172:175], v[194:197], v[96:99]
	v_mfma_f32_16x16x32_bf16 v[84:87], v[164:167], v[212:215], v[84:87]
	v_mfma_f32_16x16x32_bf16 v[80:83], v[172:175], v[212:215], v[80:83]
	v_mfma_f32_16x16x32_bf16 v[68:71], v[164:167], v[220:223], v[68:71]
	v_mfma_f32_16x16x32_bf16 v[64:67], v[172:175], v[220:223], v[64:67]
	s_setprio 0
	s_barrier
; #define PG8_STAGE(bufoff, gbase, voff) do { _Pragma("unroll") for (int _i = 0; _i < 2; ++_i) \
;         __builtin_amdgcn_global_load_lds((const unsigned*)((const char*)(gbase) + (voff)[_i]), (PG8_LAS unsigned*)(lds + (bufoff) + ldsw + _i * 8192), 16, 0, 0); } while (0)
; #define PG8_LDA(dst, b, h) do { _Pragma("unroll") for (int m = 0; m < 4; ++m) _Pragma("unroll") for (int k = 0; k < 2; ++k) dst[m][k] = *(const PG8_LAS bf16x8*)(lds + PG8_SA(b, h) + aoff + m * 2048 + k * 1024); } while (0)
; #define PG8_MMA(ai, bj, At, Bt) do { __builtin_amdgcn_s_setprio(1); _Pragma("unroll") for (int m = 0; m < 4; ++m) _Pragma("unroll") for (int n = 0; n < 2; ++n) _Pragma("unroll") for (int k = 0; k < 2; ++k) \
;         acc[ai][bj][m][n] = __builtin_amdgcn_mfma_f32_16x16x32_bf16(Bt[n][k], At[m][k], acc[ai][bj][m][n], 0, 0, 0); __builtin_amdgcn_s_setprio(0); } while (0)
; #define PG8_WAIT_V(n) asm volatile("s_waitcnt vmcnt(" #n ")" ::: "memory")
; #define PG8_WAIT_L(n) asm volatile("s_waitcnt lgkmcnt(" #n ")" ::: "memory")
; #define PG8_BAR __builtin_amdgcn_s_barrier()
; #define PG8_SCHED __builtin_amdgcn_sched_barrier(0)
; template <class Epi, class Sched, bool ALIGN_EPI = false, bool SP2 = false>
; __device__ __forceinline__ void gemm_phase(PG8_LAS unsigned char* lds, const int Kdim, const Sched& S, const Epi& E) {
;     ...
;             PG8_LDA(At, 1, 1); PG8_STAGE(PG8_SB(1, 0), b3, voffB); PG8_STAGE(PG8_SB(1, 1), b3 + hstep, voffB); PG8_STAGE(PG8_SA(1, 0), a3, voffA);
;             PG8_WAIT_V(8); PG8_WAIT_L(0); PG8_BAR; PG8_MMA(1, 0, At, B0); PG8_MMA(1, 1, At, B1); PG8_BAR; PG8_SCHED;
	s_mov_b32 m0, s60
	v_lshl_add_u64 v[142:143], v[142:143], 0, s[86:87]
	s_add_u32 s28, s28, 0xb0080
	ds_read_b128 v[176:179], v135 offset:49152
	ds_read_b128 v[180:183], v135 offset:50176
	ds_read_b128 v[184:187], v135 offset:51200
	ds_read_b128 v[194:197], v135 offset:52224
	ds_read_b128 v[198:201], v135 offset:53248
	ds_read_b128 v[212:215], v135 offset:54272
	ds_read_b128 v[216:219], v135 offset:55296
	ds_read_b128 v[220:223], v135 offset:56320
	global_load_lds_dwordx4 v[142:143], off
	v_lshl_add_u64 v[142:143], v[202:203], 0, s[86:87]
	s_mov_b32 m0, s61
	s_addc_u32 s29, s29, 0
	global_load_lds_dwordx4 v[142:143], off
	v_lshl_add_u64 v[142:143], s[28:29], 0, v[128:129]
	s_mov_b32 m0, s65
	s_nop 0
	global_load_lds_dwordx4 v[142:143], off
	v_lshl_add_u64 v[142:143], s[28:29], 0, v[132:133]
	s_mov_b32 m0, s66
	s_nop 0
	global_load_lds_dwordx4 v[142:143], off
	v_lshl_add_u64 v[142:143], v[204:205], 0, s[86:87]
	s_mov_b32 m0, s62
	s_nop 0
	global_load_lds_dwordx4 v[142:143], off
	v_lshl_add_u64 v[142:143], v[224:225], 0, s[86:87]
	s_mov_b32 m0, s63
	s_nop 0
	global_load_lds_dwordx4 v[142:143], off
	s_waitcnt vmcnt(8)
	s_waitcnt lgkmcnt(0)
	s_barrier
	s_setprio 1
	s_waitcnt lgkmcnt(0)
	v_mfma_f32_16x16x32_bf16 v[60:63], v[138:141], v[176:179], v[60:63]
	v_mfma_f32_16x16x32_bf16 v[56:59], v[152:155], v[176:179], v[56:59]
	v_mfma_f32_16x16x32_bf16 v[44:47], v[138:141], v[184:187], v[44:47]
	v_mfma_f32_16x16x32_bf16 v[40:43], v[152:155], v[184:187], v[40:43]
	v_mfma_f32_16x16x32_bf16 v[28:31], v[138:141], v[198:201], v[28:31]
	v_mfma_f32_16x16x32_bf16 v[24:27], v[152:155], v[198:201], v[24:27]
	v_mfma_f32_16x16x32_bf16 v[12:15], v[138:141], v[216:219], v[12:15]
	v_mfma_f32_16x16x32_bf16 v[8:11], v[152:155], v[216:219], v[8:11]
	v_mfma_f32_16x16x32_bf16 v[60:63], v[148:151], v[180:183], v[60:63]
	v_mfma_f32_16x16x32_bf16 v[56:59], v[156:159], v[180:183], v[56:59]
	v_mfma_f32_16x16x32_bf16 v[44:47], v[148:151], v[194:197], v[44:47]
	v_mfma_f32_16x16x32_bf16 v[40:43], v[156:159], v[194:197], v[40:43]
	v_mfma_f32_16x16x32_bf16 v[28:31], v[148:151], v[212:215], v[28:31]
	v_mfma_f32_16x16x32_bf16 v[24:27], v[156:159], v[212:215], v[24:27]
	v_mfma_f32_16x16x32_bf16 v[12:15], v[148:151], v[220:223], v[12:15]
	v_mfma_f32_16x16x32_bf16 v[8:11], v[156:159], v[220:223], v[8:11]
	v_mfma_f32_16x16x32_bf16 v[52:55], v[160:163], v[176:179], v[52:55]
	v_mfma_f32_16x16x32_bf16 v[48:51], v[168:171], v[176:179], v[48:51]
	v_mfma_f32_16x16x32_bf16 v[36:39], v[160:163], v[184:187], v[36:39]
	v_mfma_f32_16x16x32_bf16 v[32:35], v[168:171], v[184:187], v[32:35]
	v_mfma_f32_16x16x32_bf16 v[20:23], v[160:163], v[198:201], v[20:23]
	v_mfma_f32_16x16x32_bf16 v[16:19], v[168:171], v[198:201], v[16:19]
	v_mfma_f32_16x16x32_bf16 v[4:7], v[160:163], v[216:219], v[4:7]
	v_mfma_f32_16x16x32_bf16 v[0:3], v[168:171], v[216:219], v[0:3]
	v_mfma_f32_16x16x32_bf16 v[52:55], v[164:167], v[180:183], v[52:55]
	v_mfma_f32_16x16x32_bf16 v[48:51], v[172:175], v[180:183], v[48:51]
	v_mfma_f32_16x16x32_bf16 v[36:39], v[164:167], v[194:197], v[36:39]
	v_mfma_f32_16x16x32_bf16 v[32:35], v[172:175], v[194:197], v[32:35]
	v_mfma_f32_16x16x32_bf16 v[20:23], v[164:167], v[212:215], v[20:23]
	v_mfma_f32_16x16x32_bf16 v[16:19], v[172:175], v[212:215], v[16:19]
	v_mfma_f32_16x16x32_bf16 v[4:7], v[164:167], v[220:223], v[4:7]
	v_mfma_f32_16x16x32_bf16 v[0:3], v[172:175], v[220:223], v[0:3]
	s_setprio 0
	s_barrier
	s_add_u32 s26, s26, 0x100
	s_addc_u32 s27, s27, 0
	s_add_u32 s81, s81, 0x100
	s_addc_u32 s82, s82, 0
	s_mov_b32 s28, s83
